# K-loop MFMA order: consecutive MFMAs differ in one operand only (m0n0 m0n1 m1n1 m1n0 ...), fewer operand changes per MFMA; results identical
# speedup vs baseline: 1.0076x; 1.0076x over previous
.LBB0_391:
	v_add_u32_e32 v150, 0x10000, v148
	v_add_u32_e32 v151, 0x14000, v148
	ds_read_b128 v[132:135], v150
	ds_read_b128 v[136:139], v150 offset:1024
	ds_read_b128 v[140:143], v150 offset:2048
	ds_read_b128 v[152:155], v150 offset:3072
	ds_read_b128 v[156:159], v151
	ds_read_b128 v[160:163], v151 offset:1024
	ds_read_b128 v[164:167], v151 offset:2048
	ds_read_b128 v[168:171], v151 offset:3072
	s_add_i32 s12, s56, 0xfffc0080
	s_cmp_eq_u32 s29, 12
	s_cselect_b32 s60, s68, s12
	s_cselect_b32 s13, s5, s77
	s_cselect_b32 s12, s4, s76
	s_cselect_b32 s15, s7, s55
	s_cselect_b32 s14, s6, s54
	s_cselect_b32 s58, s69, s57
	s_cselect_b32 s16, s0, s8
	s_cselect_b32 s17, s1, s9
	s_cselect_b32 s18, s2, s10
	s_cselect_b32 s19, s3, s11
	s_or_b32 s59, s60, 0x80
	s_mov_b32 m0, s45
	ds_read_b128 v[172:175], v149
	ds_read_b128 v[176:179], v149 offset:1024
	ds_read_b128 v[180:183], v149 offset:2048
	ds_read_b128 v[184:187], v149 offset:3072
	ds_read_b128 v[188:191], v149 offset:4096
	ds_read_b128 v[212:215], v149 offset:5120
	ds_read_b128 v[216:219], v149 offset:6144
	ds_read_b128 v[228:231], v149 offset:7168
	buffer_load_dwordx4 v144, s[8:11], s56 offen lds
	s_mov_b32 m0, s46
	s_nop 0
	buffer_load_dwordx4 v146, s[8:11], s56 offen lds
	s_waitcnt vmcnt(8)
	s_waitcnt lgkmcnt(0)
	s_barrier
	s_setprio 1
	s_waitcnt lgkmcnt(7)
	v_mfma_f32_16x16x32_bf16 v[120:123], v[132:135], v[172:175], v[120:123]
	v_mfma_f32_16x16x32_bf16 v[112:115], v[140:143], v[172:175], v[112:115]
	s_waitcnt lgkmcnt(5)
	v_mfma_f32_16x16x32_bf16 v[88:91], v[140:143], v[180:183], v[88:91]
	v_mfma_f32_16x16x32_bf16 v[100:103], v[132:135], v[180:183], v[100:103]
	s_waitcnt lgkmcnt(3)
	v_mfma_f32_16x16x32_bf16 v[68:71], v[132:135], v[188:191], v[68:71]
	v_mfma_f32_16x16x32_bf16 v[56:59], v[140:143], v[188:191], v[56:59]
	s_waitcnt lgkmcnt(1)
	v_mfma_f32_16x16x32_bf16 v[28:31], v[140:143], v[216:219], v[28:31]
	v_mfma_f32_16x16x32_bf16 v[36:39], v[132:135], v[216:219], v[36:39]
	v_mfma_f32_16x16x32_bf16 v[120:123], v[136:139], v[176:179], v[120:123]
	v_mfma_f32_16x16x32_bf16 v[112:115], v[152:155], v[176:179], v[112:115]
	v_mfma_f32_16x16x32_bf16 v[88:91], v[152:155], v[184:187], v[88:91]
	v_mfma_f32_16x16x32_bf16 v[100:103], v[136:139], v[184:187], v[100:103]
	v_mfma_f32_16x16x32_bf16 v[68:71], v[136:139], v[212:215], v[68:71]
	v_mfma_f32_16x16x32_bf16 v[56:59], v[152:155], v[212:215], v[56:59]
	s_waitcnt lgkmcnt(0)
	v_mfma_f32_16x16x32_bf16 v[28:31], v[152:155], v[228:231], v[28:31]
	v_mfma_f32_16x16x32_bf16 v[36:39], v[136:139], v[228:231], v[36:39]
	s_setprio 0
	s_setprio 1
	v_mfma_f32_16x16x32_bf16 v[128:131], v[156:159], v[172:175], v[128:131]
	v_mfma_f32_16x16x32_bf16 v[124:127], v[164:167], v[172:175], v[124:127]
	v_mfma_f32_16x16x32_bf16 v[108:111], v[164:167], v[180:183], v[108:111]
	v_mfma_f32_16x16x32_bf16 v[116:119], v[156:159], v[180:183], v[116:119]
	v_mfma_f32_16x16x32_bf16 v[92:95], v[156:159], v[188:191], v[92:95]
	v_mfma_f32_16x16x32_bf16 v[80:83], v[164:167], v[188:191], v[80:83]
	v_mfma_f32_16x16x32_bf16 v[48:51], v[164:167], v[216:219], v[48:51]
	v_mfma_f32_16x16x32_bf16 v[64:67], v[156:159], v[216:219], v[64:67]
	v_mfma_f32_16x16x32_bf16 v[128:131], v[160:163], v[176:179], v[128:131]
	v_mfma_f32_16x16x32_bf16 v[124:127], v[168:171], v[176:179], v[124:127]
	v_mfma_f32_16x16x32_bf16 v[108:111], v[168:171], v[184:187], v[108:111]
	v_mfma_f32_16x16x32_bf16 v[116:119], v[160:163], v[184:187], v[116:119]
	v_mfma_f32_16x16x32_bf16 v[92:95], v[160:163], v[212:215], v[92:95]
	v_mfma_f32_16x16x32_bf16 v[80:83], v[168:171], v[212:215], v[80:83]
	v_mfma_f32_16x16x32_bf16 v[48:51], v[168:171], v[228:231], v[48:51]
	v_mfma_f32_16x16x32_bf16 v[64:67], v[160:163], v[228:231], v[64:67]
	s_setprio 0
	s_barrier
	s_mov_b32 m0, s92
	ds_read_b128 v[172:175], v149 offset:16384
	ds_read_b128 v[176:179], v149 offset:17408
	ds_read_b128 v[180:183], v149 offset:18432
	ds_read_b128 v[184:187], v149 offset:19456
	ds_read_b128 v[188:191], v149 offset:20480
	ds_read_b128 v[212:215], v149 offset:21504
	ds_read_b128 v[216:219], v149 offset:22528
	ds_read_b128 v[228:231], v149 offset:23552
	buffer_load_dwordx4 v145, s[12:15], s58 offen lds
	s_mov_b32 m0, s93
	s_add_i32 s61, s58, 0x40000
	buffer_load_dwordx4 v147, s[12:15], s58 offen lds
	s_mov_b32 m0, s94
	s_nop 0
	buffer_load_dwordx4 v145, s[12:15], s61 offen lds
	s_mov_b32 m0, s95
	s_nop 0
	buffer_load_dwordx4 v147, s[12:15], s61 offen lds
	s_mov_b32 m0, s44
	s_nop 0
	buffer_load_dwordx4 v144, s[16:19], s60 offen lds
	s_mov_b32 m0, s36
	s_nop 0
	buffer_load_dwordx4 v146, s[16:19], s60 offen lds
	s_waitcnt vmcnt(8)
	s_waitcnt lgkmcnt(0)
	s_barrier
	s_setprio 1
	s_waitcnt lgkmcnt(7)
	v_mfma_f32_16x16x32_bf16 v[72:75], v[132:135], v[172:175], v[72:75]
	v_mfma_f32_16x16x32_bf16 v[60:63], v[140:143], v[172:175], v[60:63]
	s_waitcnt lgkmcnt(5)
	v_mfma_f32_16x16x32_bf16 v[32:35], v[140:143], v[180:183], v[32:35]
	v_mfma_f32_16x16x32_bf16 v[40:43], v[132:135], v[180:183], v[40:43]
	s_waitcnt lgkmcnt(3)
	v_mfma_f32_16x16x32_bf16 v[16:19], v[132:135], v[188:191], v[16:19]
	v_mfma_f32_16x16x32_bf16 v[12:15], v[140:143], v[188:191], v[12:15]
	s_waitcnt lgkmcnt(1)
	v_mfma_f32_16x16x32_bf16 v[2:5], v[140:143], v[216:219], v[4:7]
	v_mfma_f32_16x16x32_bf16 v[8:11], v[132:135], v[216:219], v[8:11]
	v_mfma_f32_16x16x32_bf16 v[72:75], v[136:139], v[176:179], v[72:75]
	v_mfma_f32_16x16x32_bf16 v[60:63], v[152:155], v[176:179], v[60:63]
	v_mfma_f32_16x16x32_bf16 v[32:35], v[152:155], v[184:187], v[32:35]
	v_mfma_f32_16x16x32_bf16 v[40:43], v[136:139], v[184:187], v[40:43]
	v_mfma_f32_16x16x32_bf16 v[16:19], v[136:139], v[212:215], v[16:19]
	v_mfma_f32_16x16x32_bf16 v[12:15], v[152:155], v[212:215], v[12:15]
	s_waitcnt lgkmcnt(0)
	v_mfma_f32_16x16x32_bf16 v[2:5], v[152:155], v[228:231], v[2:5]
	v_mfma_f32_16x16x32_bf16 v[8:11], v[136:139], v[228:231], v[8:11]
	s_setprio 0
	s_setprio 1
	v_mfma_f32_16x16x32_bf16 v[96:99], v[156:159], v[172:175], v[96:99]
	v_mfma_f32_16x16x32_bf16 v[104:107], v[164:167], v[172:175], v[104:107]
	v_mfma_f32_16x16x32_bf16 v[76:79], v[164:167], v[180:183], v[76:79]
	v_mfma_f32_16x16x32_bf16 v[84:87], v[156:159], v[180:183], v[84:87]
	v_mfma_f32_16x16x32_bf16 v[52:55], v[156:159], v[188:191], v[52:55]
	v_mfma_f32_16x16x32_bf16 v[44:47], v[164:167], v[188:191], v[44:47]
	v_mfma_f32_16x16x32_bf16 v[20:23], v[164:167], v[216:219], v[20:23]
	v_mfma_f32_16x16x32_bf16 v[24:27], v[156:159], v[216:219], v[24:27]
	v_mfma_f32_16x16x32_bf16 v[96:99], v[160:163], v[176:179], v[96:99]
	v_mfma_f32_16x16x32_bf16 v[104:107], v[168:171], v[176:179], v[104:107]
	v_mfma_f32_16x16x32_bf16 v[76:79], v[168:171], v[184:187], v[76:79]
	v_mfma_f32_16x16x32_bf16 v[84:87], v[160:163], v[184:187], v[84:87]
	v_mfma_f32_16x16x32_bf16 v[52:55], v[160:163], v[212:215], v[52:55]
	v_mfma_f32_16x16x32_bf16 v[44:47], v[168:171], v[212:215], v[44:47]
	v_mfma_f32_16x16x32_bf16 v[20:23], v[168:171], v[228:231], v[20:23]
	v_mfma_f32_16x16x32_bf16 v[24:27], v[160:163], v[228:231], v[24:27]
	s_setprio 0
	s_barrier
	v_add_u32_e32 v152, 0x18000, v148
	v_add_u32_e32 v153, 0x1c000, v148
	ds_read_b128 v[132:135], v152
	ds_read_b128 v[136:139], v152 offset:1024
	ds_read_b128 v[140:143], v152 offset:2048
	ds_read_b128 v[154:157], v152 offset:3072
	ds_read_b128 v[158:161], v153
	ds_read_b128 v[162:165], v153 offset:1024
	ds_read_b128 v[166:169], v153 offset:2048
	ds_read_b128 v[170:173], v153 offset:3072
	s_add_i32 s60, s60, 0x40000
	s_mov_b32 m0, s37
	ds_read_b128 v[174:177], v149 offset:32768
	ds_read_b128 v[178:181], v149 offset:33792
	ds_read_b128 v[182:185], v149 offset:34816
	ds_read_b128 v[186:189], v149 offset:35840
	ds_read_b128 v[190:193], v149 offset:36864
	ds_read_b128 v[212:215], v149 offset:37888
	ds_read_b128 v[216:219], v149 offset:38912
	ds_read_b128 v[228:231], v149 offset:39936
	buffer_load_dwordx4 v144, s[16:19], s60 offen lds
	s_mov_b32 m0, s38
	s_nop 0
	buffer_load_dwordx4 v146, s[16:19], s60 offen lds
	s_waitcnt vmcnt(8)
	s_waitcnt lgkmcnt(0)
	s_barrier
	s_setprio 1
	s_waitcnt lgkmcnt(7)
	v_mfma_f32_16x16x32_bf16 v[120:123], v[132:135], v[174:177], v[120:123]
	v_mfma_f32_16x16x32_bf16 v[112:115], v[140:143], v[174:177], v[112:115]
	s_waitcnt lgkmcnt(5)
	v_mfma_f32_16x16x32_bf16 v[88:91], v[140:143], v[182:185], v[88:91]
	v_mfma_f32_16x16x32_bf16 v[100:103], v[132:135], v[182:185], v[100:103]
	s_waitcnt lgkmcnt(3)
	v_mfma_f32_16x16x32_bf16 v[68:71], v[132:135], v[190:193], v[68:71]
	v_mfma_f32_16x16x32_bf16 v[56:59], v[140:143], v[190:193], v[56:59]
	s_waitcnt lgkmcnt(1)
	v_mfma_f32_16x16x32_bf16 v[28:31], v[140:143], v[216:219], v[28:31]
	v_mfma_f32_16x16x32_bf16 v[36:39], v[132:135], v[216:219], v[36:39]
	v_mfma_f32_16x16x32_bf16 v[120:123], v[136:139], v[178:181], v[120:123]
	v_mfma_f32_16x16x32_bf16 v[112:115], v[154:157], v[178:181], v[112:115]
	v_mfma_f32_16x16x32_bf16 v[88:91], v[154:157], v[186:189], v[88:91]
	v_mfma_f32_16x16x32_bf16 v[100:103], v[136:139], v[186:189], v[100:103]
	v_mfma_f32_16x16x32_bf16 v[68:71], v[136:139], v[212:215], v[68:71]
	v_mfma_f32_16x16x32_bf16 v[56:59], v[154:157], v[212:215], v[56:59]
	s_waitcnt lgkmcnt(0)
	v_mfma_f32_16x16x32_bf16 v[28:31], v[154:157], v[228:231], v[28:31]
	v_mfma_f32_16x16x32_bf16 v[36:39], v[136:139], v[228:231], v[36:39]
	s_setprio 0
	s_setprio 1
	v_mfma_f32_16x16x32_bf16 v[128:131], v[158:161], v[174:177], v[128:131]
	v_mfma_f32_16x16x32_bf16 v[124:127], v[166:169], v[174:177], v[124:127]
	v_mfma_f32_16x16x32_bf16 v[108:111], v[166:169], v[182:185], v[108:111]
	v_mfma_f32_16x16x32_bf16 v[116:119], v[158:161], v[182:185], v[116:119]
	v_mfma_f32_16x16x32_bf16 v[92:95], v[158:161], v[190:193], v[92:95]
	v_mfma_f32_16x16x32_bf16 v[80:83], v[166:169], v[190:193], v[80:83]
	v_mfma_f32_16x16x32_bf16 v[48:51], v[166:169], v[216:219], v[48:51]
	v_mfma_f32_16x16x32_bf16 v[64:67], v[158:161], v[216:219], v[64:67]
	v_mfma_f32_16x16x32_bf16 v[128:131], v[162:165], v[178:181], v[128:131]
	v_mfma_f32_16x16x32_bf16 v[124:127], v[170:173], v[178:181], v[124:127]
	v_mfma_f32_16x16x32_bf16 v[108:111], v[170:173], v[186:189], v[108:111]
	v_mfma_f32_16x16x32_bf16 v[116:119], v[162:165], v[186:189], v[116:119]
	v_mfma_f32_16x16x32_bf16 v[92:95], v[162:165], v[212:215], v[92:95]
	v_mfma_f32_16x16x32_bf16 v[80:83], v[170:173], v[212:215], v[80:83]
	v_mfma_f32_16x16x32_bf16 v[48:51], v[170:173], v[228:231], v[48:51]
	v_mfma_f32_16x16x32_bf16 v[64:67], v[162:165], v[228:231], v[64:67]
	s_setprio 0
	s_barrier
; #define PG8_STAGE(bufoff, gbase, voff) do { const Src _g = (gbase); _Pragma("unroll") for (int _i = 0; _i < 2; ++_i) \
;         __builtin_amdgcn_raw_ptr_buffer_load_lds(_g.r, (LAS unsigned*)(lds + (bufoff) + ldsw + _i * 8192), 16, (voff)[_i], _g.o, 0, 0); } while (0)
; #define PG8_WAIT_V(n) asm volatile("s_waitcnt vmcnt(" #n ")" ::: "memory")
; template <class Epi, bool ALIGN_EPI, bool SP2, class Hook>
; __device__ __forceinline__ void gemm_phase(LAS unsigned char* lds, const Gemm g, const StaticOrder& S, const Epi& E, Acc& acc, const bool fresh, const Hook& H, const int wave_id) {
;     ...
;         for (int t = t0; t < nt; t += 2) {
;             const bool last = (t == nt - 2);
;             const Src a1 = cA + (size_t)(t + 1) * kstep;
;             const Src a2 = last ? nA : cA + (size_t)(t + 2) * kstep, b2 = last ? nB : cB + (size_t)(t + 2) * kstep;
;             const Src a3 = a2 + kstep, b3 = b2 + kstep;
;             if (last && has_next) H(nxt);
;             if constexpr (SP2) {
;             PG8_TRIP_SP2(PG8_WAIT_V(8));
;             } else {
;             PG8_LDB(B0, 0, 0); PG8_SCHED; PG8_LDA(At, 0, 0); PG8_STAGE(PG8_SA(1, 1), a1 + hstepA, voffA);
;             PG8_WAIT_L(8); PG8_BAR; PG8_WAIT_L(0); PG8_MMA(0, 0, At, B0); PG8_BAR; PG8_SCHED;
;             PG8_LDB(B1, 0, 1); PG8_STAGE(PG8_SB(0, 0), b2, voffB);
;             PG8_BAR; PG8_WAIT_L(0); PG8_MMA(0, 1, At, B1); PG8_BAR;
;             PG8_LDA(At, 0, 1); PG8_STAGE(PG8_SA(0, 0), a2, voffA);
;             PG8_BAR; PG8_WAIT_L(0); PG8_MMA(1, 0, At, B0); PG8_BAR; PG8_SCHED;
;             PG8_STAGE(PG8_SB(0, 1), b2 + hstep, voffB);
;             PG8_WAIT_V(6); PG8_BAR; PG8_MMA(1, 1, At, B1); PG8_BAR;
;             PG8_LDB(B0, 1, 0); PG8_SCHED; PG8_LDA(At, 1, 0); PG8_STAGE(PG8_SA(0, 1), a2 + hstepA, voffA);
;             PG8_WAIT_L(8); PG8_BAR; PG8_WAIT_L(0); PG8_MMA(0, 0, At, B0); PG8_BAR; PG8_SCHED;
;             PG8_LDB(B1, 1, 1); PG8_STAGE(PG8_SB(1, 0), b3, voffB);
;             PG8_BAR; PG8_WAIT_L(0); PG8_MMA(0, 1, At, B1); PG8_BAR;
;             PG8_LDA(At, 1, 1); PG8_STAGE(PG8_SA(1, 0), a3, voffA);
;             PG8_BAR; PG8_WAIT_L(0); PG8_MMA(1, 0, At, B0); PG8_BAR; PG8_SCHED;
;             PG8_STAGE(PG8_SB(1, 1), b3 + hstep, voffB);
;             PG8_WAIT_V(6); PG8_BAR; PG8_MMA(1, 1, At, B1); PG8_BAR;
;             }
;         }
;         if constexpr (ALIGN_EPI) { if (wr == 0) PG8_BAR; }
	s_mov_b32 m0, s39
	s_or_b32 s60, s58, 0x80
	ds_read_b128 v[174:177], v149 offset:49152
	ds_read_b128 v[178:181], v149 offset:50176
	ds_read_b128 v[182:185], v149 offset:51200
	ds_read_b128 v[186:189], v149 offset:52224
	ds_read_b128 v[190:193], v149 offset:53248
	ds_read_b128 v[212:215], v149 offset:54272
	ds_read_b128 v[216:219], v149 offset:55296
	ds_read_b128 v[228:231], v149 offset:56320
	buffer_load_dwordx4 v145, s[12:15], s60 offen lds
	s_mov_b32 m0, s40
	s_add_i32 s58, s58, 0x40080
	buffer_load_dwordx4 v147, s[12:15], s60 offen lds
	s_mov_b32 m0, s43
	s_nop 0
	buffer_load_dwordx4 v145, s[12:15], s58 offen lds
	s_mov_b32 m0, s42
	s_nop 0
	buffer_load_dwordx4 v147, s[12:15], s58 offen lds
	s_mov_b32 m0, s41
	s_nop 0
	buffer_load_dwordx4 v144, s[16:19], s59 offen lds
	s_mov_b32 m0, s33
	s_nop 0
	buffer_load_dwordx4 v146, s[16:19], s59 offen lds
	s_waitcnt vmcnt(8)
	s_waitcnt lgkmcnt(0)
	s_barrier
	s_setprio 1
	s_waitcnt lgkmcnt(7)
	v_mfma_f32_16x16x32_bf16 v[72:75], v[132:135], v[174:177], v[72:75]
	v_mfma_f32_16x16x32_bf16 v[60:63], v[140:143], v[174:177], v[60:63]
	s_waitcnt lgkmcnt(5)
	v_mfma_f32_16x16x32_bf16 v[32:35], v[140:143], v[182:185], v[32:35]
	v_mfma_f32_16x16x32_bf16 v[40:43], v[132:135], v[182:185], v[40:43]
	s_waitcnt lgkmcnt(3)
	v_mfma_f32_16x16x32_bf16 v[16:19], v[132:135], v[190:193], v[16:19]
	v_mfma_f32_16x16x32_bf16 v[12:15], v[140:143], v[190:193], v[12:15]
	s_waitcnt lgkmcnt(1)
	v_mfma_f32_16x16x32_bf16 v[2:5], v[140:143], v[216:219], v[2:5]
	v_mfma_f32_16x16x32_bf16 v[6:9], v[132:135], v[216:219], v[8:11]
	v_mfma_f32_16x16x32_bf16 v[72:75], v[136:139], v[178:181], v[72:75]
	v_mfma_f32_16x16x32_bf16 v[60:63], v[154:157], v[178:181], v[60:63]
	v_mfma_f32_16x16x32_bf16 v[32:35], v[154:157], v[186:189], v[32:35]
	v_mfma_f32_16x16x32_bf16 v[40:43], v[136:139], v[186:189], v[40:43]
	v_mfma_f32_16x16x32_bf16 v[16:19], v[136:139], v[212:215], v[16:19]
	v_mfma_f32_16x16x32_bf16 v[12:15], v[154:157], v[212:215], v[12:15]
	s_waitcnt lgkmcnt(0)
	v_mfma_f32_16x16x32_bf16 v[4:7], v[154:157], v[228:231], v[2:5]
	v_mfma_f32_16x16x32_bf16 v[8:11], v[136:139], v[228:231], v[6:9]
	s_setprio 0
	s_setprio 1
	v_mfma_f32_16x16x32_bf16 v[96:99], v[158:161], v[174:177], v[96:99]
	v_mfma_f32_16x16x32_bf16 v[104:107], v[166:169], v[174:177], v[104:107]
	v_mfma_f32_16x16x32_bf16 v[76:79], v[166:169], v[182:185], v[76:79]
	v_mfma_f32_16x16x32_bf16 v[84:87], v[158:161], v[182:185], v[84:87]
	v_mfma_f32_16x16x32_bf16 v[52:55], v[158:161], v[190:193], v[52:55]
	v_mfma_f32_16x16x32_bf16 v[44:47], v[166:169], v[190:193], v[44:47]
	v_mfma_f32_16x16x32_bf16 v[20:23], v[166:169], v[216:219], v[20:23]
	v_mfma_f32_16x16x32_bf16 v[24:27], v[158:161], v[216:219], v[24:27]
	v_mfma_f32_16x16x32_bf16 v[96:99], v[162:165], v[178:181], v[96:99]
	v_mfma_f32_16x16x32_bf16 v[104:107], v[170:173], v[178:181], v[104:107]
	v_mfma_f32_16x16x32_bf16 v[76:79], v[170:173], v[186:189], v[76:79]
	v_mfma_f32_16x16x32_bf16 v[84:87], v[162:165], v[186:189], v[84:87]
	v_mfma_f32_16x16x32_bf16 v[52:55], v[162:165], v[212:215], v[52:55]
	v_mfma_f32_16x16x32_bf16 v[44:47], v[170:173], v[212:215], v[44:47]
	v_mfma_f32_16x16x32_bf16 v[20:23], v[170:173], v[228:231], v[20:23]
	v_mfma_f32_16x16x32_bf16 v[24:27], v[162:165], v[228:231], v[24:27]
	s_setprio 0
	s_barrier
	s_add_i32 s29, s29, 2
	s_addk_i32 s56, 0x100
	s_addk_i32 s57, 0x100
	s_cmp_gt_u32 s29, 13
	s_cbranch_scc0 .LBB0_391
	v_readlane_b32 s8, v251, 45
	v_readlane_b32 s9, v251, 46
	s_and_b64 vcc, exec, s[8:9]
	s_cbranch_vccz .LBB0_394
	s_barrier

.LBB0_779:
	v_add_u32_e32 v0, 0x10000, v230
	s_waitcnt vmcnt(0)
	ds_read_b128 v[130:133], v0
	ds_read_b128 v[134:137], v0 offset:1024
	ds_read_b128 v[138:141], v0 offset:2048
	ds_read_b128 v[142:145], v0 offset:3072
	v_add_u32_e32 v0, 0x14000, v230
	ds_read_b128 v[146:149], v0
	ds_read_b128 v[150:153], v0 offset:1024
	ds_read_b128 v[154:157], v0 offset:2048
	ds_read_b128 v[158:161], v0 offset:3072
	s_add_i32 s12, s2, 0xfffe0080
	s_cmp_eq_u32 s63, 4
	s_cselect_b32 s66, s60, s12
	s_cselect_b32 s13, s53, s77
	s_cselect_b32 s12, s52, s76
	s_cselect_b32 s15, s55, s7
	s_cselect_b32 s14, s54, s6
	s_cselect_b32 s64, s61, s3
	s_cselect_b32 s16, s34, s8
	s_cselect_b32 s17, s35, s9
	s_cselect_b32 s18, s50, s10
	s_cselect_b32 s19, s51, s11
	s_or_b32 s65, s66, 0x80
	s_mov_b32 m0, s45
	ds_read_b128 v[162:165], v231
	ds_read_b128 v[166:169], v231 offset:1024
	ds_read_b128 v[170:173], v231 offset:2048
	ds_read_b128 v[174:177], v231 offset:3072
	ds_read_b128 v[178:181], v231 offset:4096
	ds_read_b128 v[182:185], v231 offset:5120
	ds_read_b128 v[186:189], v231 offset:6144
	ds_read_b128 v[190:193], v231 offset:7168
	buffer_load_dwordx4 v199, s[8:11], s2 offen lds
	s_mov_b32 m0, s46
	s_nop 0
	buffer_load_dwordx4 v228, s[8:11], s2 offen lds
	s_waitcnt vmcnt(8)
	s_waitcnt lgkmcnt(0)
	s_barrier
	s_setprio 1
	s_waitcnt lgkmcnt(7)
	v_mfma_f32_16x16x32_bf16 v[126:129], v[130:133], v[162:165], v[126:129]
	v_mfma_f32_16x16x32_bf16 v[122:125], v[138:141], v[162:165], v[122:125]
	s_waitcnt lgkmcnt(5)
	v_mfma_f32_16x16x32_bf16 v[114:117], v[138:141], v[170:173], v[114:117]
	v_mfma_f32_16x16x32_bf16 v[118:121], v[130:133], v[170:173], v[118:121]
	s_waitcnt lgkmcnt(3)
	v_mfma_f32_16x16x32_bf16 v[110:113], v[130:133], v[178:181], v[110:113]
	v_mfma_f32_16x16x32_bf16 v[106:109], v[138:141], v[178:181], v[106:109]
	s_waitcnt lgkmcnt(1)
	v_mfma_f32_16x16x32_bf16 v[98:101], v[138:141], v[186:189], v[98:101]
	v_mfma_f32_16x16x32_bf16 v[102:105], v[130:133], v[186:189], v[102:105]
	v_mfma_f32_16x16x32_bf16 v[126:129], v[134:137], v[166:169], v[126:129]
	v_mfma_f32_16x16x32_bf16 v[122:125], v[142:145], v[166:169], v[122:125]
	v_mfma_f32_16x16x32_bf16 v[114:117], v[142:145], v[174:177], v[114:117]
	v_mfma_f32_16x16x32_bf16 v[118:121], v[134:137], v[174:177], v[118:121]
	v_mfma_f32_16x16x32_bf16 v[110:113], v[134:137], v[182:185], v[110:113]
	v_mfma_f32_16x16x32_bf16 v[106:109], v[142:145], v[182:185], v[106:109]
	s_waitcnt lgkmcnt(0)
	v_mfma_f32_16x16x32_bf16 v[98:101], v[142:145], v[190:193], v[98:101]
	v_mfma_f32_16x16x32_bf16 v[102:105], v[134:137], v[190:193], v[102:105]
	s_setprio 0
	s_setprio 1
	v_mfma_f32_16x16x32_bf16 v[94:97], v[146:149], v[162:165], v[94:97]
	v_mfma_f32_16x16x32_bf16 v[90:93], v[154:157], v[162:165], v[90:93]
	v_mfma_f32_16x16x32_bf16 v[82:85], v[154:157], v[170:173], v[82:85]
	v_mfma_f32_16x16x32_bf16 v[86:89], v[146:149], v[170:173], v[86:89]
	v_mfma_f32_16x16x32_bf16 v[78:81], v[146:149], v[178:181], v[78:81]
	v_mfma_f32_16x16x32_bf16 v[74:77], v[154:157], v[178:181], v[74:77]
	v_mfma_f32_16x16x32_bf16 v[66:69], v[154:157], v[186:189], v[66:69]
	v_mfma_f32_16x16x32_bf16 v[70:73], v[146:149], v[186:189], v[70:73]
	v_mfma_f32_16x16x32_bf16 v[94:97], v[150:153], v[166:169], v[94:97]
	v_mfma_f32_16x16x32_bf16 v[90:93], v[158:161], v[166:169], v[90:93]
	v_mfma_f32_16x16x32_bf16 v[82:85], v[158:161], v[174:177], v[82:85]
	v_mfma_f32_16x16x32_bf16 v[86:89], v[150:153], v[174:177], v[86:89]
	v_mfma_f32_16x16x32_bf16 v[78:81], v[150:153], v[182:185], v[78:81]
	v_mfma_f32_16x16x32_bf16 v[74:77], v[158:161], v[182:185], v[74:77]
	v_mfma_f32_16x16x32_bf16 v[66:69], v[158:161], v[190:193], v[66:69]
	v_mfma_f32_16x16x32_bf16 v[70:73], v[150:153], v[190:193], v[70:73]
	s_setprio 0
	s_barrier
	s_mov_b32 m0, s92
	ds_read_b128 v[162:165], v231 offset:16384
	ds_read_b128 v[166:169], v231 offset:17408
	ds_read_b128 v[170:173], v231 offset:18432
	ds_read_b128 v[174:177], v231 offset:19456
	ds_read_b128 v[178:181], v231 offset:20480
	ds_read_b128 v[182:185], v231 offset:21504
	ds_read_b128 v[186:189], v231 offset:22528
	ds_read_b128 v[190:193], v231 offset:23552
	buffer_load_dwordx4 v227, s[12:15], s64 offen lds
	s_mov_b32 m0, s93
	s_add_i32 s67, s64, 0x20000
	buffer_load_dwordx4 v229, s[12:15], s64 offen lds
	s_mov_b32 m0, s94
	s_nop 0
	buffer_load_dwordx4 v227, s[12:15], s67 offen lds
	s_mov_b32 m0, s95
	s_nop 0
	buffer_load_dwordx4 v229, s[12:15], s67 offen lds
	s_mov_b32 m0, s44
	s_nop 0
	buffer_load_dwordx4 v199, s[16:19], s66 offen lds
	s_mov_b32 m0, s36
	s_nop 0
	buffer_load_dwordx4 v228, s[16:19], s66 offen lds
	s_waitcnt vmcnt(8)
	s_waitcnt lgkmcnt(0)
	s_barrier
	s_setprio 1
	s_waitcnt lgkmcnt(7)
	v_mfma_f32_16x16x32_bf16 v[62:65], v[130:133], v[162:165], v[62:65]
	v_mfma_f32_16x16x32_bf16 v[58:61], v[138:141], v[162:165], v[58:61]
	s_waitcnt lgkmcnt(5)
	v_mfma_f32_16x16x32_bf16 v[50:53], v[138:141], v[170:173], v[50:53]
	v_mfma_f32_16x16x32_bf16 v[54:57], v[130:133], v[170:173], v[54:57]
	s_waitcnt lgkmcnt(3)
	v_mfma_f32_16x16x32_bf16 v[46:49], v[130:133], v[178:181], v[46:49]
	v_mfma_f32_16x16x32_bf16 v[42:45], v[138:141], v[178:181], v[42:45]
	s_waitcnt lgkmcnt(1)
	v_mfma_f32_16x16x32_bf16 v[34:37], v[138:141], v[186:189], v[34:37]
	v_mfma_f32_16x16x32_bf16 v[38:41], v[130:133], v[186:189], v[38:41]
	v_mfma_f32_16x16x32_bf16 v[62:65], v[134:137], v[166:169], v[62:65]
	v_mfma_f32_16x16x32_bf16 v[58:61], v[142:145], v[166:169], v[58:61]
	v_mfma_f32_16x16x32_bf16 v[50:53], v[142:145], v[174:177], v[50:53]
	v_mfma_f32_16x16x32_bf16 v[54:57], v[134:137], v[174:177], v[54:57]
	v_mfma_f32_16x16x32_bf16 v[46:49], v[134:137], v[182:185], v[46:49]
	v_mfma_f32_16x16x32_bf16 v[42:45], v[142:145], v[182:185], v[42:45]
	s_waitcnt lgkmcnt(0)
	v_mfma_f32_16x16x32_bf16 v[34:37], v[142:145], v[190:193], v[34:37]
	v_mfma_f32_16x16x32_bf16 v[38:41], v[134:137], v[190:193], v[38:41]
	s_setprio 0
	s_setprio 1
	v_mfma_f32_16x16x32_bf16 v[30:33], v[146:149], v[162:165], v[30:33]
	v_mfma_f32_16x16x32_bf16 v[26:29], v[154:157], v[162:165], v[26:29]
	v_mfma_f32_16x16x32_bf16 v[18:21], v[154:157], v[170:173], v[18:21]
	v_mfma_f32_16x16x32_bf16 v[22:25], v[146:149], v[170:173], v[22:25]
	v_mfma_f32_16x16x32_bf16 v[14:17], v[146:149], v[178:181], v[14:17]
	v_mfma_f32_16x16x32_bf16 v[10:13], v[154:157], v[178:181], v[10:13]
	v_mfma_f32_16x16x32_bf16 v[2:5], v[154:157], v[186:189], v[2:5]
	v_mfma_f32_16x16x32_bf16 v[6:9], v[146:149], v[186:189], v[6:9]
	v_mfma_f32_16x16x32_bf16 v[30:33], v[150:153], v[166:169], v[30:33]
	v_mfma_f32_16x16x32_bf16 v[26:29], v[158:161], v[166:169], v[26:29]
	v_mfma_f32_16x16x32_bf16 v[18:21], v[158:161], v[174:177], v[18:21]
	v_mfma_f32_16x16x32_bf16 v[22:25], v[150:153], v[174:177], v[22:25]
	v_mfma_f32_16x16x32_bf16 v[14:17], v[150:153], v[182:185], v[14:17]
	v_mfma_f32_16x16x32_bf16 v[10:13], v[158:161], v[182:185], v[10:13]
	v_mfma_f32_16x16x32_bf16 v[2:5], v[158:161], v[190:193], v[2:5]
	v_mfma_f32_16x16x32_bf16 v[6:9], v[150:153], v[190:193], v[6:9]
	s_setprio 0
	s_barrier
	v_add_u32_e32 v0, 0x18000, v230
	ds_read_b128 v[130:133], v0
	ds_read_b128 v[134:137], v0 offset:1024
	ds_read_b128 v[138:141], v0 offset:2048
	ds_read_b128 v[142:145], v0 offset:3072
	v_add_u32_e32 v0, 0x1c000, v230
	ds_read_b128 v[146:149], v0
	ds_read_b128 v[150:153], v0 offset:1024
	ds_read_b128 v[154:157], v0 offset:2048
	ds_read_b128 v[158:161], v0 offset:3072
	s_add_i32 s66, s66, 0x20000
	s_mov_b32 m0, s37
	ds_read_b128 v[162:165], v231 offset:32768
	ds_read_b128 v[166:169], v231 offset:33792
	ds_read_b128 v[170:173], v231 offset:34816
	ds_read_b128 v[174:177], v231 offset:35840
	ds_read_b128 v[178:181], v231 offset:36864
	ds_read_b128 v[182:185], v231 offset:37888
	ds_read_b128 v[186:189], v231 offset:38912
	ds_read_b128 v[190:193], v231 offset:39936
	buffer_load_dwordx4 v199, s[16:19], s66 offen lds
	s_mov_b32 m0, s38
	s_nop 0
	buffer_load_dwordx4 v228, s[16:19], s66 offen lds
	s_waitcnt vmcnt(8)
	s_waitcnt lgkmcnt(0)
	s_barrier
	s_setprio 1
	s_waitcnt lgkmcnt(7)
	v_mfma_f32_16x16x32_bf16 v[126:129], v[130:133], v[162:165], v[126:129]
	v_mfma_f32_16x16x32_bf16 v[122:125], v[138:141], v[162:165], v[122:125]
	s_waitcnt lgkmcnt(5)
	v_mfma_f32_16x16x32_bf16 v[114:117], v[138:141], v[170:173], v[114:117]
	v_mfma_f32_16x16x32_bf16 v[118:121], v[130:133], v[170:173], v[118:121]
	s_waitcnt lgkmcnt(3)
	v_mfma_f32_16x16x32_bf16 v[110:113], v[130:133], v[178:181], v[110:113]
	v_mfma_f32_16x16x32_bf16 v[106:109], v[138:141], v[178:181], v[106:109]
	s_waitcnt lgkmcnt(1)
	v_mfma_f32_16x16x32_bf16 v[98:101], v[138:141], v[186:189], v[98:101]
	v_mfma_f32_16x16x32_bf16 v[102:105], v[130:133], v[186:189], v[102:105]
	v_mfma_f32_16x16x32_bf16 v[126:129], v[134:137], v[166:169], v[126:129]
	v_mfma_f32_16x16x32_bf16 v[122:125], v[142:145], v[166:169], v[122:125]
	v_mfma_f32_16x16x32_bf16 v[114:117], v[142:145], v[174:177], v[114:117]
	v_mfma_f32_16x16x32_bf16 v[118:121], v[134:137], v[174:177], v[118:121]
	v_mfma_f32_16x16x32_bf16 v[110:113], v[134:137], v[182:185], v[110:113]
	v_mfma_f32_16x16x32_bf16 v[106:109], v[142:145], v[182:185], v[106:109]
	s_waitcnt lgkmcnt(0)
	v_mfma_f32_16x16x32_bf16 v[98:101], v[142:145], v[190:193], v[98:101]
	v_mfma_f32_16x16x32_bf16 v[102:105], v[134:137], v[190:193], v[102:105]
	s_setprio 0
	s_setprio 1
	v_mfma_f32_16x16x32_bf16 v[94:97], v[146:149], v[162:165], v[94:97]
	v_mfma_f32_16x16x32_bf16 v[90:93], v[154:157], v[162:165], v[90:93]
	v_mfma_f32_16x16x32_bf16 v[82:85], v[154:157], v[170:173], v[82:85]
	v_mfma_f32_16x16x32_bf16 v[86:89], v[146:149], v[170:173], v[86:89]
	v_mfma_f32_16x16x32_bf16 v[78:81], v[146:149], v[178:181], v[78:81]
	v_mfma_f32_16x16x32_bf16 v[74:77], v[154:157], v[178:181], v[74:77]
	v_mfma_f32_16x16x32_bf16 v[66:69], v[154:157], v[186:189], v[66:69]
	v_mfma_f32_16x16x32_bf16 v[70:73], v[146:149], v[186:189], v[70:73]
	v_mfma_f32_16x16x32_bf16 v[94:97], v[150:153], v[166:169], v[94:97]
	v_mfma_f32_16x16x32_bf16 v[90:93], v[158:161], v[166:169], v[90:93]
	v_mfma_f32_16x16x32_bf16 v[82:85], v[158:161], v[174:177], v[82:85]
	v_mfma_f32_16x16x32_bf16 v[86:89], v[150:153], v[174:177], v[86:89]
	v_mfma_f32_16x16x32_bf16 v[78:81], v[150:153], v[182:185], v[78:81]
	v_mfma_f32_16x16x32_bf16 v[74:77], v[158:161], v[182:185], v[74:77]
	v_mfma_f32_16x16x32_bf16 v[66:69], v[158:161], v[190:193], v[66:69]
	v_mfma_f32_16x16x32_bf16 v[70:73], v[150:153], v[190:193], v[70:73]
	s_setprio 0
	s_barrier
; #define PG8_STAGE(bufoff, gbase, voff) do { const Src _g = (gbase); _Pragma("unroll") for (int _i = 0; _i < 2; ++_i) \
;         __builtin_amdgcn_raw_ptr_buffer_load_lds(_g.r, (LAS unsigned*)(lds + (bufoff) + ldsw + _i * 8192), 16, (voff)[_i], _g.o, 0, 0); } while (0)
; #define PG8_WAIT_V(n) asm volatile("s_waitcnt vmcnt(" #n ")" ::: "memory")
; template <class Epi, bool ALIGN_EPI, bool SP2, class Hook>
; __device__ __forceinline__ void gemm_phase(LAS unsigned char* lds, const Gemm g, const StaticOrder& S, const Epi& E, Acc& acc, const bool fresh, const Hook& H, const int wave_id) {
;     ...
;         for (int t = t0; t < nt; t += 2) {
;             const bool last = (t == nt - 2);
;             const Src a1 = cA + (size_t)(t + 1) * kstep;
;             const Src a2 = last ? nA : cA + (size_t)(t + 2) * kstep, b2 = last ? nB : cB + (size_t)(t + 2) * kstep;
;             const Src a3 = a2 + kstep, b3 = b2 + kstep;
;             if (last && has_next) H(nxt);
;             if constexpr (SP2) {
;             PG8_TRIP_SP2(PG8_WAIT_V(8));
;             } else {
;             PG8_LDB(B0, 0, 0); PG8_SCHED; PG8_LDA(At, 0, 0); PG8_STAGE(PG8_SA(1, 1), a1 + hstepA, voffA);
;             PG8_WAIT_L(8); PG8_BAR; PG8_WAIT_L(0); PG8_MMA(0, 0, At, B0); PG8_BAR; PG8_SCHED;
;             PG8_LDB(B1, 0, 1); PG8_STAGE(PG8_SB(0, 0), b2, voffB);
;             PG8_BAR; PG8_WAIT_L(0); PG8_MMA(0, 1, At, B1); PG8_BAR;
;             PG8_LDA(At, 0, 1); PG8_STAGE(PG8_SA(0, 0), a2, voffA);
;             PG8_BAR; PG8_WAIT_L(0); PG8_MMA(1, 0, At, B0); PG8_BAR; PG8_SCHED;
;             PG8_STAGE(PG8_SB(0, 1), b2 + hstep, voffB);
;             PG8_WAIT_V(6); PG8_BAR; PG8_MMA(1, 1, At, B1); PG8_BAR;
;             PG8_LDB(B0, 1, 0); PG8_SCHED; PG8_LDA(At, 1, 0); PG8_STAGE(PG8_SA(0, 1), a2 + hstepA, voffA);
;             PG8_WAIT_L(8); PG8_BAR; PG8_WAIT_L(0); PG8_MMA(0, 0, At, B0); PG8_BAR; PG8_SCHED;
;             PG8_LDB(B1, 1, 1); PG8_STAGE(PG8_SB(1, 0), b3, voffB);
;             PG8_BAR; PG8_WAIT_L(0); PG8_MMA(0, 1, At, B1); PG8_BAR;
;             PG8_LDA(At, 1, 1); PG8_STAGE(PG8_SA(1, 0), a3, voffA);
;             PG8_BAR; PG8_WAIT_L(0); PG8_MMA(1, 0, At, B0); PG8_BAR; PG8_SCHED;
;             PG8_STAGE(PG8_SB(1, 1), b3 + hstep, voffB);
;             PG8_WAIT_V(6); PG8_BAR; PG8_MMA(1, 1, At, B1); PG8_BAR;
;             }
;         }
;         if constexpr (ALIGN_EPI) { if (wr == 0) PG8_BAR; }
	s_mov_b32 m0, s39
	s_or_b32 s66, s64, 0x80
	ds_read_b128 v[162:165], v231 offset:49152
	ds_read_b128 v[166:169], v231 offset:50176
	ds_read_b128 v[170:173], v231 offset:51200
	ds_read_b128 v[174:177], v231 offset:52224
	ds_read_b128 v[178:181], v231 offset:53248
	ds_read_b128 v[182:185], v231 offset:54272
	ds_read_b128 v[186:189], v231 offset:55296
	ds_read_b128 v[190:193], v231 offset:56320
	buffer_load_dwordx4 v227, s[12:15], s66 offen lds
	s_mov_b32 m0, s40
	s_add_i32 s64, s64, 0x20080
	buffer_load_dwordx4 v229, s[12:15], s66 offen lds
	s_mov_b32 m0, s43
	s_nop 0
	buffer_load_dwordx4 v227, s[12:15], s64 offen lds
	s_mov_b32 m0, s42
	s_nop 0
	buffer_load_dwordx4 v229, s[12:15], s64 offen lds
	s_mov_b32 m0, s41
	s_nop 0
	buffer_load_dwordx4 v199, s[16:19], s65 offen lds
	s_mov_b32 m0, s33
	s_nop 0
	buffer_load_dwordx4 v228, s[16:19], s65 offen lds
	s_waitcnt vmcnt(8)
	s_waitcnt lgkmcnt(0)
	s_barrier
	s_setprio 1
	s_waitcnt lgkmcnt(7)
	v_mfma_f32_16x16x32_bf16 v[62:65], v[130:133], v[162:165], v[62:65]
	v_mfma_f32_16x16x32_bf16 v[58:61], v[138:141], v[162:165], v[58:61]
	s_waitcnt lgkmcnt(5)
	v_mfma_f32_16x16x32_bf16 v[50:53], v[138:141], v[170:173], v[50:53]
	v_mfma_f32_16x16x32_bf16 v[54:57], v[130:133], v[170:173], v[54:57]
	s_waitcnt lgkmcnt(3)
	v_mfma_f32_16x16x32_bf16 v[46:49], v[130:133], v[178:181], v[46:49]
	v_mfma_f32_16x16x32_bf16 v[42:45], v[138:141], v[178:181], v[42:45]
	s_waitcnt lgkmcnt(1)
	v_mfma_f32_16x16x32_bf16 v[34:37], v[138:141], v[186:189], v[34:37]
	v_mfma_f32_16x16x32_bf16 v[38:41], v[130:133], v[186:189], v[38:41]
	v_mfma_f32_16x16x32_bf16 v[62:65], v[134:137], v[166:169], v[62:65]
	v_mfma_f32_16x16x32_bf16 v[58:61], v[142:145], v[166:169], v[58:61]
	v_mfma_f32_16x16x32_bf16 v[50:53], v[142:145], v[174:177], v[50:53]
	v_mfma_f32_16x16x32_bf16 v[54:57], v[134:137], v[174:177], v[54:57]
	v_mfma_f32_16x16x32_bf16 v[46:49], v[134:137], v[182:185], v[46:49]
	v_mfma_f32_16x16x32_bf16 v[42:45], v[142:145], v[182:185], v[42:45]
	s_waitcnt lgkmcnt(0)
	v_mfma_f32_16x16x32_bf16 v[34:37], v[142:145], v[190:193], v[34:37]
	v_mfma_f32_16x16x32_bf16 v[38:41], v[134:137], v[190:193], v[38:41]
	s_setprio 0
	s_setprio 1
	v_mfma_f32_16x16x32_bf16 v[30:33], v[146:149], v[162:165], v[30:33]
	v_mfma_f32_16x16x32_bf16 v[26:29], v[154:157], v[162:165], v[26:29]
	v_mfma_f32_16x16x32_bf16 v[18:21], v[154:157], v[170:173], v[18:21]
	v_mfma_f32_16x16x32_bf16 v[22:25], v[146:149], v[170:173], v[22:25]
	v_mfma_f32_16x16x32_bf16 v[14:17], v[146:149], v[178:181], v[14:17]
	v_mfma_f32_16x16x32_bf16 v[10:13], v[154:157], v[178:181], v[10:13]
	v_mfma_f32_16x16x32_bf16 v[2:5], v[154:157], v[186:189], v[2:5]
	v_mfma_f32_16x16x32_bf16 v[6:9], v[146:149], v[186:189], v[6:9]
	v_mfma_f32_16x16x32_bf16 v[30:33], v[150:153], v[166:169], v[30:33]
	v_mfma_f32_16x16x32_bf16 v[26:29], v[158:161], v[166:169], v[26:29]
	v_mfma_f32_16x16x32_bf16 v[18:21], v[158:161], v[174:177], v[18:21]
	v_mfma_f32_16x16x32_bf16 v[22:25], v[150:153], v[174:177], v[22:25]
	v_mfma_f32_16x16x32_bf16 v[14:17], v[150:153], v[182:185], v[14:17]
	v_mfma_f32_16x16x32_bf16 v[10:13], v[158:161], v[182:185], v[10:13]
	v_mfma_f32_16x16x32_bf16 v[2:5], v[158:161], v[190:193], v[2:5]
	v_mfma_f32_16x16x32_bf16 v[6:9], v[150:153], v[190:193], v[6:9]
	s_setprio 0
	s_barrier
	s_add_i32 s63, s63, 2
	s_addk_i32 s2, 0x100
	s_addk_i32 s3, 0x100
	s_cmp_gt_u32 s63, 5
	s_cbranch_scc0 .LBB0_779
	v_readlane_b32 s2, v251, 45
	v_readlane_b32 s3, v251, 46
	s_and_b64 vcc, exec, s[2:3]
	s_cbranch_vccz .LBB0_782
	s_barrier

.LBB0_1029:
.LBB0_1030:
	v_add_u32_e32 v0, 0x10000, v230
	s_waitcnt vmcnt(0)
	ds_read_b128 v[130:133], v0
	ds_read_b128 v[134:137], v0 offset:1024
	ds_read_b128 v[138:141], v0 offset:2048
	ds_read_b128 v[142:145], v0 offset:3072
	v_add_u32_e32 v0, 0x14000, v230
	ds_read_b128 v[146:149], v0
	ds_read_b128 v[150:153], v0 offset:1024
	ds_read_b128 v[154:157], v0 offset:2048
	ds_read_b128 v[158:161], v0 offset:3072
	s_lshl_b32 s55, s20, 7
	s_add_i32 s18, s73, s55
	s_and_b64 s[12:13], s[16:17], exec
	s_cselect_b32 s13, s31, s9
	s_cselect_b32 s12, s30, s8
	s_cselect_b32 s15, s35, s11
	s_cselect_b32 s14, s34, s10
	s_cselect_b32 s56, s68, s18
	s_add_i32 s21, s74, s55
	s_and_b64 s[16:17], s[16:17], exec
	s_cselect_b32 s54, s69, s21
	s_cselect_b32 s17, s51, s77
	s_cselect_b32 s16, s50, s76
	s_cselect_b32 s19, s53, s7
	s_cselect_b32 s18, s52, s6
	s_or_b32 s21, s56, 0x80
	s_or_b32 s57, s54, 0x80
	s_add_i32 s55, s55, s75
	s_mov_b32 m0, s45
	ds_read_b128 v[162:165], v231
	ds_read_b128 v[166:169], v231 offset:1024
	ds_read_b128 v[170:173], v231 offset:2048
	ds_read_b128 v[174:177], v231 offset:3072
	ds_read_b128 v[178:181], v231 offset:4096
	ds_read_b128 v[182:185], v231 offset:5120
	ds_read_b128 v[186:189], v231 offset:6144
	ds_read_b128 v[190:193], v231 offset:7168
	buffer_load_dwordx4 v199, s[8:11], s55 offen lds
	s_mov_b32 m0, s46
	s_nop 0
	buffer_load_dwordx4 v228, s[8:11], s55 offen lds
	s_waitcnt vmcnt(8)
	s_waitcnt lgkmcnt(0)
	s_barrier
	s_setprio 1
	s_waitcnt lgkmcnt(7)
	v_mfma_f32_16x16x32_bf16 v[126:129], v[130:133], v[162:165], v[126:129]
	v_mfma_f32_16x16x32_bf16 v[122:125], v[138:141], v[162:165], v[122:125]
	s_waitcnt lgkmcnt(5)
	v_mfma_f32_16x16x32_bf16 v[114:117], v[138:141], v[170:173], v[114:117]
	v_mfma_f32_16x16x32_bf16 v[118:121], v[130:133], v[170:173], v[118:121]
	s_waitcnt lgkmcnt(3)
	v_mfma_f32_16x16x32_bf16 v[110:113], v[130:133], v[178:181], v[110:113]
	v_mfma_f32_16x16x32_bf16 v[106:109], v[138:141], v[178:181], v[106:109]
	s_waitcnt lgkmcnt(1)
	v_mfma_f32_16x16x32_bf16 v[98:101], v[138:141], v[186:189], v[98:101]
	v_mfma_f32_16x16x32_bf16 v[102:105], v[130:133], v[186:189], v[102:105]
	v_mfma_f32_16x16x32_bf16 v[126:129], v[134:137], v[166:169], v[126:129]
	v_mfma_f32_16x16x32_bf16 v[122:125], v[142:145], v[166:169], v[122:125]
	v_mfma_f32_16x16x32_bf16 v[114:117], v[142:145], v[174:177], v[114:117]
	v_mfma_f32_16x16x32_bf16 v[118:121], v[134:137], v[174:177], v[118:121]
	v_mfma_f32_16x16x32_bf16 v[110:113], v[134:137], v[182:185], v[110:113]
	v_mfma_f32_16x16x32_bf16 v[106:109], v[142:145], v[182:185], v[106:109]
	s_waitcnt lgkmcnt(0)
	v_mfma_f32_16x16x32_bf16 v[98:101], v[142:145], v[190:193], v[98:101]
	v_mfma_f32_16x16x32_bf16 v[102:105], v[134:137], v[190:193], v[102:105]
	s_setprio 0
	s_setprio 1
	v_mfma_f32_16x16x32_bf16 v[94:97], v[146:149], v[162:165], v[94:97]
	v_mfma_f32_16x16x32_bf16 v[90:93], v[154:157], v[162:165], v[90:93]
	v_mfma_f32_16x16x32_bf16 v[82:85], v[154:157], v[170:173], v[82:85]
	v_mfma_f32_16x16x32_bf16 v[86:89], v[146:149], v[170:173], v[86:89]
	v_mfma_f32_16x16x32_bf16 v[78:81], v[146:149], v[178:181], v[78:81]
	v_mfma_f32_16x16x32_bf16 v[74:77], v[154:157], v[178:181], v[74:77]
	v_mfma_f32_16x16x32_bf16 v[66:69], v[154:157], v[186:189], v[66:69]
	v_mfma_f32_16x16x32_bf16 v[70:73], v[146:149], v[186:189], v[70:73]
	v_mfma_f32_16x16x32_bf16 v[94:97], v[150:153], v[166:169], v[94:97]
	v_mfma_f32_16x16x32_bf16 v[90:93], v[158:161], v[166:169], v[90:93]
	v_mfma_f32_16x16x32_bf16 v[82:85], v[158:161], v[174:177], v[82:85]
	v_mfma_f32_16x16x32_bf16 v[86:89], v[150:153], v[174:177], v[86:89]
	v_mfma_f32_16x16x32_bf16 v[78:81], v[150:153], v[182:185], v[78:81]
	v_mfma_f32_16x16x32_bf16 v[74:77], v[158:161], v[182:185], v[74:77]
	v_mfma_f32_16x16x32_bf16 v[66:69], v[158:161], v[190:193], v[66:69]
	v_mfma_f32_16x16x32_bf16 v[70:73], v[150:153], v[190:193], v[70:73]
	s_setprio 0
	s_barrier
	s_mov_b32 m0, s92
	ds_read_b128 v[162:165], v231 offset:16384
	ds_read_b128 v[166:169], v231 offset:17408
	ds_read_b128 v[170:173], v231 offset:18432
	ds_read_b128 v[174:177], v231 offset:19456
	ds_read_b128 v[178:181], v231 offset:20480
	ds_read_b128 v[182:185], v231 offset:21504
	ds_read_b128 v[186:189], v231 offset:22528
	ds_read_b128 v[190:193], v231 offset:23552
	buffer_load_dwordx4 v227, s[16:19], s54 offen lds
	s_mov_b32 m0, s93
	s_add_i32 s55, s54, 0x20000
	buffer_load_dwordx4 v229, s[16:19], s54 offen lds
	s_mov_b32 m0, s94
	s_nop 0
	buffer_load_dwordx4 v227, s[16:19], s55 offen lds
	s_mov_b32 m0, s95
	s_nop 0
	buffer_load_dwordx4 v229, s[16:19], s55 offen lds
	s_mov_b32 m0, s44
	s_nop 0
	buffer_load_dwordx4 v199, s[12:15], s56 offen lds
	s_mov_b32 m0, s36
	s_nop 0
	buffer_load_dwordx4 v228, s[12:15], s56 offen lds
	s_waitcnt vmcnt(8)
	s_waitcnt lgkmcnt(0)
	s_barrier
	s_setprio 1
	s_waitcnt lgkmcnt(7)
	v_mfma_f32_16x16x32_bf16 v[62:65], v[130:133], v[162:165], v[62:65]
	v_mfma_f32_16x16x32_bf16 v[58:61], v[138:141], v[162:165], v[58:61]
	s_waitcnt lgkmcnt(5)
	v_mfma_f32_16x16x32_bf16 v[50:53], v[138:141], v[170:173], v[50:53]
	v_mfma_f32_16x16x32_bf16 v[54:57], v[130:133], v[170:173], v[54:57]
	s_waitcnt lgkmcnt(3)
	v_mfma_f32_16x16x32_bf16 v[46:49], v[130:133], v[178:181], v[46:49]
	v_mfma_f32_16x16x32_bf16 v[42:45], v[138:141], v[178:181], v[42:45]
	s_waitcnt lgkmcnt(1)
	v_mfma_f32_16x16x32_bf16 v[34:37], v[138:141], v[186:189], v[34:37]
	v_mfma_f32_16x16x32_bf16 v[38:41], v[130:133], v[186:189], v[38:41]
	v_mfma_f32_16x16x32_bf16 v[62:65], v[134:137], v[166:169], v[62:65]
	v_mfma_f32_16x16x32_bf16 v[58:61], v[142:145], v[166:169], v[58:61]
	v_mfma_f32_16x16x32_bf16 v[50:53], v[142:145], v[174:177], v[50:53]
	v_mfma_f32_16x16x32_bf16 v[54:57], v[134:137], v[174:177], v[54:57]
	v_mfma_f32_16x16x32_bf16 v[46:49], v[134:137], v[182:185], v[46:49]
	v_mfma_f32_16x16x32_bf16 v[42:45], v[142:145], v[182:185], v[42:45]
	s_waitcnt lgkmcnt(0)
	v_mfma_f32_16x16x32_bf16 v[34:37], v[142:145], v[190:193], v[34:37]
	v_mfma_f32_16x16x32_bf16 v[38:41], v[134:137], v[190:193], v[38:41]
	s_setprio 0
	s_setprio 1
	v_mfma_f32_16x16x32_bf16 v[30:33], v[146:149], v[162:165], v[30:33]
	v_mfma_f32_16x16x32_bf16 v[26:29], v[154:157], v[162:165], v[26:29]
	v_mfma_f32_16x16x32_bf16 v[18:21], v[154:157], v[170:173], v[18:21]
	v_mfma_f32_16x16x32_bf16 v[22:25], v[146:149], v[170:173], v[22:25]
	v_mfma_f32_16x16x32_bf16 v[14:17], v[146:149], v[178:181], v[14:17]
	v_mfma_f32_16x16x32_bf16 v[10:13], v[154:157], v[178:181], v[10:13]
	v_mfma_f32_16x16x32_bf16 v[2:5], v[154:157], v[186:189], v[2:5]
	v_mfma_f32_16x16x32_bf16 v[6:9], v[146:149], v[186:189], v[6:9]
	v_mfma_f32_16x16x32_bf16 v[30:33], v[150:153], v[166:169], v[30:33]
	v_mfma_f32_16x16x32_bf16 v[26:29], v[158:161], v[166:169], v[26:29]
	v_mfma_f32_16x16x32_bf16 v[18:21], v[158:161], v[174:177], v[18:21]
	v_mfma_f32_16x16x32_bf16 v[22:25], v[150:153], v[174:177], v[22:25]
	v_mfma_f32_16x16x32_bf16 v[14:17], v[150:153], v[182:185], v[14:17]
	v_mfma_f32_16x16x32_bf16 v[10:13], v[158:161], v[182:185], v[10:13]
	v_mfma_f32_16x16x32_bf16 v[2:5], v[158:161], v[190:193], v[2:5]
	v_mfma_f32_16x16x32_bf16 v[6:9], v[150:153], v[190:193], v[6:9]
	s_setprio 0
	s_barrier
	v_add_u32_e32 v0, 0x18000, v230
	ds_read_b128 v[130:133], v0
	ds_read_b128 v[134:137], v0 offset:1024
	ds_read_b128 v[138:141], v0 offset:2048
	ds_read_b128 v[142:145], v0 offset:3072
	v_add_u32_e32 v0, 0x1c000, v230
	ds_read_b128 v[146:149], v0
	ds_read_b128 v[150:153], v0 offset:1024
	ds_read_b128 v[154:157], v0 offset:2048
	ds_read_b128 v[158:161], v0 offset:3072
	s_add_i32 s56, s56, 0x20000
	s_mov_b32 m0, s37
	ds_read_b128 v[162:165], v231 offset:32768
	ds_read_b128 v[166:169], v231 offset:33792
	ds_read_b128 v[170:173], v231 offset:34816
	ds_read_b128 v[174:177], v231 offset:35840
	ds_read_b128 v[178:181], v231 offset:36864
	ds_read_b128 v[182:185], v231 offset:37888
	ds_read_b128 v[186:189], v231 offset:38912
	ds_read_b128 v[190:193], v231 offset:39936
	buffer_load_dwordx4 v199, s[12:15], s56 offen lds
	s_mov_b32 m0, s38
	s_nop 0
	buffer_load_dwordx4 v228, s[12:15], s56 offen lds
	s_waitcnt vmcnt(8)
	s_waitcnt lgkmcnt(0)
	s_barrier
	s_setprio 1
	s_waitcnt lgkmcnt(7)
	v_mfma_f32_16x16x32_bf16 v[126:129], v[130:133], v[162:165], v[126:129]
	v_mfma_f32_16x16x32_bf16 v[122:125], v[138:141], v[162:165], v[122:125]
	s_waitcnt lgkmcnt(5)
	v_mfma_f32_16x16x32_bf16 v[114:117], v[138:141], v[170:173], v[114:117]
	v_mfma_f32_16x16x32_bf16 v[118:121], v[130:133], v[170:173], v[118:121]
	s_waitcnt lgkmcnt(3)
	v_mfma_f32_16x16x32_bf16 v[110:113], v[130:133], v[178:181], v[110:113]
	v_mfma_f32_16x16x32_bf16 v[106:109], v[138:141], v[178:181], v[106:109]
	s_waitcnt lgkmcnt(1)
	v_mfma_f32_16x16x32_bf16 v[98:101], v[138:141], v[186:189], v[98:101]
	v_mfma_f32_16x16x32_bf16 v[102:105], v[130:133], v[186:189], v[102:105]
	v_mfma_f32_16x16x32_bf16 v[126:129], v[134:137], v[166:169], v[126:129]
	v_mfma_f32_16x16x32_bf16 v[122:125], v[142:145], v[166:169], v[122:125]
	v_mfma_f32_16x16x32_bf16 v[114:117], v[142:145], v[174:177], v[114:117]
	v_mfma_f32_16x16x32_bf16 v[118:121], v[134:137], v[174:177], v[118:121]
	v_mfma_f32_16x16x32_bf16 v[110:113], v[134:137], v[182:185], v[110:113]
	v_mfma_f32_16x16x32_bf16 v[106:109], v[142:145], v[182:185], v[106:109]
	s_waitcnt lgkmcnt(0)
	v_mfma_f32_16x16x32_bf16 v[98:101], v[142:145], v[190:193], v[98:101]
	v_mfma_f32_16x16x32_bf16 v[102:105], v[134:137], v[190:193], v[102:105]
	s_setprio 0
	s_setprio 1
	v_mfma_f32_16x16x32_bf16 v[94:97], v[146:149], v[162:165], v[94:97]
	v_mfma_f32_16x16x32_bf16 v[90:93], v[154:157], v[162:165], v[90:93]
	v_mfma_f32_16x16x32_bf16 v[82:85], v[154:157], v[170:173], v[82:85]
	v_mfma_f32_16x16x32_bf16 v[86:89], v[146:149], v[170:173], v[86:89]
	v_mfma_f32_16x16x32_bf16 v[78:81], v[146:149], v[178:181], v[78:81]
	v_mfma_f32_16x16x32_bf16 v[74:77], v[154:157], v[178:181], v[74:77]
	v_mfma_f32_16x16x32_bf16 v[66:69], v[154:157], v[186:189], v[66:69]
	v_mfma_f32_16x16x32_bf16 v[70:73], v[146:149], v[186:189], v[70:73]
	v_mfma_f32_16x16x32_bf16 v[94:97], v[150:153], v[166:169], v[94:97]
	v_mfma_f32_16x16x32_bf16 v[90:93], v[158:161], v[166:169], v[90:93]
	v_mfma_f32_16x16x32_bf16 v[82:85], v[158:161], v[174:177], v[82:85]
	v_mfma_f32_16x16x32_bf16 v[86:89], v[150:153], v[174:177], v[86:89]
	v_mfma_f32_16x16x32_bf16 v[78:81], v[150:153], v[182:185], v[78:81]
	v_mfma_f32_16x16x32_bf16 v[74:77], v[158:161], v[182:185], v[74:77]
	v_mfma_f32_16x16x32_bf16 v[66:69], v[158:161], v[190:193], v[66:69]
	v_mfma_f32_16x16x32_bf16 v[70:73], v[150:153], v[190:193], v[70:73]
	s_setprio 0
	s_barrier
; #define PG8_STAGE(bufoff, gbase, voff) do { const Src _g = (gbase); _Pragma("unroll") for (int _i = 0; _i < 2; ++_i) \
;         __builtin_amdgcn_raw_ptr_buffer_load_lds(_g.r, (LAS unsigned*)(lds + (bufoff) + ldsw + _i * 8192), 16, (voff)[_i], _g.o, 0, 0); } while (0)
; #define PG8_WAIT_V(n) asm volatile("s_waitcnt vmcnt(" #n ")" ::: "memory")
; #define PG8_BAR __builtin_amdgcn_s_barrier()
; template <class Epi, bool ALIGN_EPI, bool SP2, class Hook>
; __device__ __forceinline__ void gemm_phase(LAS unsigned char* lds, const Gemm g, const StaticOrder& S, const Epi& E, Acc& acc, const bool fresh, const Hook& H, const int wave_id) {
;     ...
;         for (int t = t0; t < nt; t += 2) {
;             const bool last = (t == nt - 2);
;             const Src a1 = cA + (size_t)(t + 1) * kstep;
;             const Src a2 = last ? nA : cA + (size_t)(t + 2) * kstep, b2 = last ? nB : cB + (size_t)(t + 2) * kstep;
;             const Src a3 = a2 + kstep, b3 = b2 + kstep;
;             if (last && has_next) H(nxt);
;             if constexpr (SP2) {
;             PG8_TRIP_SP2(PG8_WAIT_V(8));
;             } else {
;             PG8_LDB(B0, 0, 0); PG8_SCHED; PG8_LDA(At, 0, 0); PG8_STAGE(PG8_SA(1, 1), a1 + hstepA, voffA);
;             PG8_WAIT_L(8); PG8_BAR; PG8_WAIT_L(0); PG8_MMA(0, 0, At, B0); PG8_BAR; PG8_SCHED;
;             PG8_LDB(B1, 0, 1); PG8_STAGE(PG8_SB(0, 0), b2, voffB);
;             PG8_BAR; PG8_WAIT_L(0); PG8_MMA(0, 1, At, B1); PG8_BAR;
;             PG8_LDA(At, 0, 1); PG8_STAGE(PG8_SA(0, 0), a2, voffA);
;             PG8_BAR; PG8_WAIT_L(0); PG8_MMA(1, 0, At, B0); PG8_BAR; PG8_SCHED;
;             PG8_STAGE(PG8_SB(0, 1), b2 + hstep, voffB);
;             PG8_WAIT_V(6); PG8_BAR; PG8_MMA(1, 1, At, B1); PG8_BAR;
;             PG8_LDB(B0, 1, 0); PG8_SCHED; PG8_LDA(At, 1, 0); PG8_STAGE(PG8_SA(0, 1), a2 + hstepA, voffA);
;             PG8_WAIT_L(8); PG8_BAR; PG8_WAIT_L(0); PG8_MMA(0, 0, At, B0); PG8_BAR; PG8_SCHED;
;             PG8_LDB(B1, 1, 1); PG8_STAGE(PG8_SB(1, 0), b3, voffB);
;             PG8_BAR; PG8_WAIT_L(0); PG8_MMA(0, 1, At, B1); PG8_BAR;
;             PG8_LDA(At, 1, 1); PG8_STAGE(PG8_SA(1, 0), a3, voffA);
;             PG8_BAR; PG8_WAIT_L(0); PG8_MMA(1, 0, At, B0); PG8_BAR; PG8_SCHED;
;             PG8_STAGE(PG8_SB(1, 1), b3 + hstep, voffB);
;             PG8_WAIT_V(6); PG8_BAR; PG8_MMA(1, 1, At, B1); PG8_BAR;
;             }
;         }
	s_mov_b32 m0, s39
	ds_read_b128 v[162:165], v231 offset:49152
	ds_read_b128 v[166:169], v231 offset:50176
	ds_read_b128 v[170:173], v231 offset:51200
	ds_read_b128 v[174:177], v231 offset:52224
	ds_read_b128 v[178:181], v231 offset:53248
	ds_read_b128 v[182:185], v231 offset:54272
	ds_read_b128 v[186:189], v231 offset:55296
	ds_read_b128 v[190:193], v231 offset:56320
	buffer_load_dwordx4 v227, s[16:19], s57 offen lds
	s_mov_b32 m0, s40
	s_add_i32 s54, s54, 0x20080
	buffer_load_dwordx4 v229, s[16:19], s57 offen lds
	s_mov_b32 m0, s43
	s_nop 0
	buffer_load_dwordx4 v227, s[16:19], s54 offen lds
	s_mov_b32 m0, s42
	s_nop 0
	buffer_load_dwordx4 v229, s[16:19], s54 offen lds
	s_mov_b32 m0, s41
	s_nop 0
	buffer_load_dwordx4 v199, s[12:15], s21 offen lds
	s_mov_b32 m0, s33
	s_nop 0
	buffer_load_dwordx4 v228, s[12:15], s21 offen lds
	s_waitcnt vmcnt(8)
	s_waitcnt lgkmcnt(0)
	s_barrier
	s_setprio 1
	s_waitcnt lgkmcnt(7)
	v_mfma_f32_16x16x32_bf16 v[62:65], v[130:133], v[162:165], v[62:65]
	v_mfma_f32_16x16x32_bf16 v[58:61], v[138:141], v[162:165], v[58:61]
	s_waitcnt lgkmcnt(5)
	v_mfma_f32_16x16x32_bf16 v[50:53], v[138:141], v[170:173], v[50:53]
	v_mfma_f32_16x16x32_bf16 v[54:57], v[130:133], v[170:173], v[54:57]
	s_waitcnt lgkmcnt(3)
	v_mfma_f32_16x16x32_bf16 v[46:49], v[130:133], v[178:181], v[46:49]
	v_mfma_f32_16x16x32_bf16 v[42:45], v[138:141], v[178:181], v[42:45]
	s_waitcnt lgkmcnt(1)
	v_mfma_f32_16x16x32_bf16 v[34:37], v[138:141], v[186:189], v[34:37]
	v_mfma_f32_16x16x32_bf16 v[38:41], v[130:133], v[186:189], v[38:41]
	v_mfma_f32_16x16x32_bf16 v[62:65], v[134:137], v[166:169], v[62:65]
	v_mfma_f32_16x16x32_bf16 v[58:61], v[142:145], v[166:169], v[58:61]
	v_mfma_f32_16x16x32_bf16 v[50:53], v[142:145], v[174:177], v[50:53]
	v_mfma_f32_16x16x32_bf16 v[54:57], v[134:137], v[174:177], v[54:57]
	v_mfma_f32_16x16x32_bf16 v[46:49], v[134:137], v[182:185], v[46:49]
	v_mfma_f32_16x16x32_bf16 v[42:45], v[142:145], v[182:185], v[42:45]
	s_waitcnt lgkmcnt(0)
	v_mfma_f32_16x16x32_bf16 v[34:37], v[142:145], v[190:193], v[34:37]
	v_mfma_f32_16x16x32_bf16 v[38:41], v[134:137], v[190:193], v[38:41]
	s_setprio 0
	s_setprio 1
	v_mfma_f32_16x16x32_bf16 v[30:33], v[146:149], v[162:165], v[30:33]
	v_mfma_f32_16x16x32_bf16 v[26:29], v[154:157], v[162:165], v[26:29]
	v_mfma_f32_16x16x32_bf16 v[18:21], v[154:157], v[170:173], v[18:21]
	v_mfma_f32_16x16x32_bf16 v[22:25], v[146:149], v[170:173], v[22:25]
	v_mfma_f32_16x16x32_bf16 v[14:17], v[146:149], v[178:181], v[14:17]
	v_mfma_f32_16x16x32_bf16 v[10:13], v[154:157], v[178:181], v[10:13]
	v_mfma_f32_16x16x32_bf16 v[2:5], v[154:157], v[186:189], v[2:5]
	v_mfma_f32_16x16x32_bf16 v[6:9], v[146:149], v[186:189], v[6:9]
	v_mfma_f32_16x16x32_bf16 v[30:33], v[150:153], v[166:169], v[30:33]
	v_mfma_f32_16x16x32_bf16 v[26:29], v[158:161], v[166:169], v[26:29]
	v_mfma_f32_16x16x32_bf16 v[18:21], v[158:161], v[174:177], v[18:21]
	v_mfma_f32_16x16x32_bf16 v[22:25], v[150:153], v[174:177], v[22:25]
	v_mfma_f32_16x16x32_bf16 v[14:17], v[150:153], v[182:185], v[14:17]
	v_mfma_f32_16x16x32_bf16 v[10:13], v[158:161], v[182:185], v[10:13]
	v_mfma_f32_16x16x32_bf16 v[2:5], v[158:161], v[190:193], v[2:5]
	v_mfma_f32_16x16x32_bf16 v[6:9], v[150:153], v[190:193], v[6:9]
	s_setprio 0
	s_barrier
	s_add_i32 s12, s20, 2
	s_cmp_gt_u32 s20, 5
	s_cbranch_scc1 .LBB0_1032
	s_mov_b32 s20, s12
	s_branch .LBB0_951

.LBB0_1235:
	v_add_u32_e32 v142, 0x10000, v161
	v_add_u32_e32 v163, 0x14000, v161
	ds_read_b128 v[130:133], v142
	ds_read_b128 v[134:137], v142 offset:1024
	ds_read_b128 v[138:141], v142 offset:2048
	ds_read_b128 v[142:145], v142 offset:3072
	ds_read_b128 v[146:149], v163
	ds_read_b128 v[150:153], v163 offset:1024
	ds_read_b128 v[154:157], v163 offset:2048
	ds_read_b128 v[164:167], v163 offset:3072
	s_add_i32 s16, s2, 0xfffc0080
	s_cmp_eq_u32 s59, 12
	s_cselect_b32 s62, s55, s16
	s_cselect_b32 s17, s31, s9
	s_cselect_b32 s16, s30, s8
	s_cselect_b32 s19, s35, s51
	s_cselect_b32 s18, s34, s50
	s_cselect_b32 s60, s56, s3
	s_cselect_b32 s20, s26, s12
	s_cselect_b32 s21, s27, s13
	s_cselect_b32 s22, s28, s14
	s_cselect_b32 s23, s29, s15
	s_or_b32 s61, s62, 0x80
	s_mov_b32 m0, s45
	ds_read_b128 v[168:171], v162
	ds_read_b128 v[172:175], v162 offset:1024
	ds_read_b128 v[176:179], v162 offset:2048
	ds_read_b128 v[180:183], v162 offset:3072
	ds_read_b128 v[184:187], v162 offset:4096
	ds_read_b128 v[188:191], v162 offset:5120
	ds_read_b128 v[192:195], v162 offset:6144
	ds_read_b128 v[200:203], v162 offset:7168
	buffer_load_dwordx4 v0, s[12:15], s2 offen lds
	s_mov_b32 m0, s46
	s_nop 0
	buffer_load_dwordx4 v159, s[12:15], s2 offen lds
	s_waitcnt vmcnt(8)
	s_waitcnt lgkmcnt(0)
	s_barrier
	s_setprio 1
	s_waitcnt lgkmcnt(7)
	v_mfma_f32_16x16x32_bf16 v[126:129], v[130:133], v[168:171], v[126:129]
	v_mfma_f32_16x16x32_bf16 v[122:125], v[138:141], v[168:171], v[122:125]
	s_waitcnt lgkmcnt(5)
	v_mfma_f32_16x16x32_bf16 v[106:109], v[138:141], v[176:179], v[106:109]
	v_mfma_f32_16x16x32_bf16 v[110:113], v[130:133], v[176:179], v[110:113]
	s_waitcnt lgkmcnt(3)
	v_mfma_f32_16x16x32_bf16 v[94:97], v[130:133], v[184:187], v[94:97]
	v_mfma_f32_16x16x32_bf16 v[90:93], v[138:141], v[184:187], v[90:93]
	s_waitcnt lgkmcnt(1)
	v_mfma_f32_16x16x32_bf16 v[74:77], v[138:141], v[192:195], v[74:77]
	v_mfma_f32_16x16x32_bf16 v[78:81], v[130:133], v[192:195], v[78:81]
	v_mfma_f32_16x16x32_bf16 v[126:129], v[134:137], v[172:175], v[126:129]
	v_mfma_f32_16x16x32_bf16 v[122:125], v[142:145], v[172:175], v[122:125]
	v_mfma_f32_16x16x32_bf16 v[106:109], v[142:145], v[180:183], v[106:109]
	v_mfma_f32_16x16x32_bf16 v[110:113], v[134:137], v[180:183], v[110:113]
	v_mfma_f32_16x16x32_bf16 v[94:97], v[134:137], v[188:191], v[94:97]
	v_mfma_f32_16x16x32_bf16 v[90:93], v[142:145], v[188:191], v[90:93]
	s_waitcnt lgkmcnt(0)
	v_mfma_f32_16x16x32_bf16 v[74:77], v[142:145], v[200:203], v[74:77]
	v_mfma_f32_16x16x32_bf16 v[78:81], v[134:137], v[200:203], v[78:81]
	s_setprio 0
	s_setprio 1
	v_mfma_f32_16x16x32_bf16 v[118:121], v[146:149], v[168:171], v[118:121]
	v_mfma_f32_16x16x32_bf16 v[114:117], v[154:157], v[168:171], v[114:117]
	v_mfma_f32_16x16x32_bf16 v[98:101], v[154:157], v[176:179], v[98:101]
	v_mfma_f32_16x16x32_bf16 v[102:105], v[146:149], v[176:179], v[102:105]
	v_mfma_f32_16x16x32_bf16 v[86:89], v[146:149], v[184:187], v[86:89]
	v_mfma_f32_16x16x32_bf16 v[82:85], v[154:157], v[184:187], v[82:85]
	v_mfma_f32_16x16x32_bf16 v[66:69], v[154:157], v[192:195], v[66:69]
	v_mfma_f32_16x16x32_bf16 v[70:73], v[146:149], v[192:195], v[70:73]
	v_mfma_f32_16x16x32_bf16 v[118:121], v[150:153], v[172:175], v[118:121]
	v_mfma_f32_16x16x32_bf16 v[114:117], v[164:167], v[172:175], v[114:117]
	v_mfma_f32_16x16x32_bf16 v[98:101], v[164:167], v[180:183], v[98:101]
	v_mfma_f32_16x16x32_bf16 v[102:105], v[150:153], v[180:183], v[102:105]
	v_mfma_f32_16x16x32_bf16 v[86:89], v[150:153], v[188:191], v[86:89]
	v_mfma_f32_16x16x32_bf16 v[82:85], v[164:167], v[188:191], v[82:85]
	v_mfma_f32_16x16x32_bf16 v[66:69], v[164:167], v[200:203], v[66:69]
	v_mfma_f32_16x16x32_bf16 v[70:73], v[150:153], v[200:203], v[70:73]
	s_setprio 0
	s_barrier
	s_mov_b32 m0, s92
	ds_read_b128 v[168:171], v162 offset:16384
	ds_read_b128 v[172:175], v162 offset:17408
	ds_read_b128 v[176:179], v162 offset:18432
	ds_read_b128 v[180:183], v162 offset:19456
	ds_read_b128 v[184:187], v162 offset:20480
	ds_read_b128 v[188:191], v162 offset:21504
	ds_read_b128 v[192:195], v162 offset:22528
	ds_read_b128 v[200:203], v162 offset:23552
	buffer_load_dwordx4 v158, s[16:19], s60 offen lds
	s_mov_b32 m0, s93
	s_add_i32 s63, s60, 0x40000
	buffer_load_dwordx4 v160, s[16:19], s60 offen lds
	s_mov_b32 m0, s94
	s_nop 0
	buffer_load_dwordx4 v158, s[16:19], s63 offen lds
	s_mov_b32 m0, s95
	s_nop 0
	buffer_load_dwordx4 v160, s[16:19], s63 offen lds
	s_mov_b32 m0, s44
	s_nop 0
	buffer_load_dwordx4 v0, s[20:23], s62 offen lds
	s_mov_b32 m0, s36
	s_nop 0
	buffer_load_dwordx4 v159, s[20:23], s62 offen lds
	s_waitcnt vmcnt(8)
	s_waitcnt lgkmcnt(0)
	s_barrier
	s_setprio 1
	s_waitcnt lgkmcnt(7)
	v_mfma_f32_16x16x32_bf16 v[62:65], v[130:133], v[168:171], v[62:65]
	v_mfma_f32_16x16x32_bf16 v[58:61], v[138:141], v[168:171], v[58:61]
	s_waitcnt lgkmcnt(5)
	v_mfma_f32_16x16x32_bf16 v[42:45], v[138:141], v[176:179], v[42:45]
	v_mfma_f32_16x16x32_bf16 v[46:49], v[130:133], v[176:179], v[46:49]
	s_waitcnt lgkmcnt(3)
	v_mfma_f32_16x16x32_bf16 v[30:33], v[130:133], v[184:187], v[30:33]
	v_mfma_f32_16x16x32_bf16 v[26:29], v[138:141], v[184:187], v[26:29]
	s_waitcnt lgkmcnt(1)
	v_mfma_f32_16x16x32_bf16 v[10:13], v[138:141], v[192:195], v[10:13]
	v_mfma_f32_16x16x32_bf16 v[14:17], v[130:133], v[192:195], v[14:17]
	v_mfma_f32_16x16x32_bf16 v[62:65], v[134:137], v[172:175], v[62:65]
	v_mfma_f32_16x16x32_bf16 v[58:61], v[142:145], v[172:175], v[58:61]
	v_mfma_f32_16x16x32_bf16 v[42:45], v[142:145], v[180:183], v[42:45]
	v_mfma_f32_16x16x32_bf16 v[46:49], v[134:137], v[180:183], v[46:49]
	v_mfma_f32_16x16x32_bf16 v[30:33], v[134:137], v[188:191], v[30:33]
	v_mfma_f32_16x16x32_bf16 v[26:29], v[142:145], v[188:191], v[26:29]
	s_waitcnt lgkmcnt(0)
	v_mfma_f32_16x16x32_bf16 v[10:13], v[142:145], v[200:203], v[10:13]
	v_mfma_f32_16x16x32_bf16 v[14:17], v[134:137], v[200:203], v[14:17]
	s_setprio 0
	s_setprio 1
	v_mfma_f32_16x16x32_bf16 v[54:57], v[146:149], v[168:171], v[54:57]
	v_mfma_f32_16x16x32_bf16 v[50:53], v[154:157], v[168:171], v[50:53]
	v_mfma_f32_16x16x32_bf16 v[34:37], v[154:157], v[176:179], v[34:37]
	v_mfma_f32_16x16x32_bf16 v[38:41], v[146:149], v[176:179], v[38:41]
	v_mfma_f32_16x16x32_bf16 v[22:25], v[146:149], v[184:187], v[22:25]
	v_mfma_f32_16x16x32_bf16 v[18:21], v[154:157], v[184:187], v[18:21]
	v_mfma_f32_16x16x32_bf16 v[2:5], v[154:157], v[192:195], v[2:5]
	v_mfma_f32_16x16x32_bf16 v[6:9], v[146:149], v[192:195], v[6:9]
	v_mfma_f32_16x16x32_bf16 v[54:57], v[150:153], v[172:175], v[54:57]
	v_mfma_f32_16x16x32_bf16 v[50:53], v[164:167], v[172:175], v[50:53]
	v_mfma_f32_16x16x32_bf16 v[34:37], v[164:167], v[180:183], v[34:37]
	v_mfma_f32_16x16x32_bf16 v[38:41], v[150:153], v[180:183], v[38:41]
	v_mfma_f32_16x16x32_bf16 v[22:25], v[150:153], v[188:191], v[22:25]
	v_mfma_f32_16x16x32_bf16 v[18:21], v[164:167], v[188:191], v[18:21]
	v_mfma_f32_16x16x32_bf16 v[2:5], v[164:167], v[200:203], v[2:5]
	v_mfma_f32_16x16x32_bf16 v[6:9], v[150:153], v[200:203], v[6:9]
	s_setprio 0
	s_barrier
	v_add_u32_e32 v142, 0x18000, v161
	v_add_u32_e32 v163, 0x1c000, v161
	ds_read_b128 v[130:133], v142
	ds_read_b128 v[134:137], v142 offset:1024
	ds_read_b128 v[138:141], v142 offset:2048
	ds_read_b128 v[142:145], v142 offset:3072
	ds_read_b128 v[146:149], v163
	ds_read_b128 v[150:153], v163 offset:1024
	ds_read_b128 v[154:157], v163 offset:2048
	ds_read_b128 v[164:167], v163 offset:3072
	s_add_i32 s62, s62, 0x40000
	s_mov_b32 m0, s37
	ds_read_b128 v[168:171], v162 offset:32768
	ds_read_b128 v[172:175], v162 offset:33792
	ds_read_b128 v[176:179], v162 offset:34816
	ds_read_b128 v[180:183], v162 offset:35840
	ds_read_b128 v[184:187], v162 offset:36864
	ds_read_b128 v[188:191], v162 offset:37888
	ds_read_b128 v[192:195], v162 offset:38912
	ds_read_b128 v[200:203], v162 offset:39936
	buffer_load_dwordx4 v0, s[20:23], s62 offen lds
	s_mov_b32 m0, s38
	s_nop 0
	buffer_load_dwordx4 v159, s[20:23], s62 offen lds
	s_waitcnt vmcnt(8)
	s_waitcnt lgkmcnt(0)
	s_barrier
	s_setprio 1
	s_waitcnt lgkmcnt(7)
	v_mfma_f32_16x16x32_bf16 v[126:129], v[130:133], v[168:171], v[126:129]
	v_mfma_f32_16x16x32_bf16 v[122:125], v[138:141], v[168:171], v[122:125]
	s_waitcnt lgkmcnt(5)
	v_mfma_f32_16x16x32_bf16 v[106:109], v[138:141], v[176:179], v[106:109]
	v_mfma_f32_16x16x32_bf16 v[110:113], v[130:133], v[176:179], v[110:113]
	s_waitcnt lgkmcnt(3)
	v_mfma_f32_16x16x32_bf16 v[94:97], v[130:133], v[184:187], v[94:97]
	v_mfma_f32_16x16x32_bf16 v[90:93], v[138:141], v[184:187], v[90:93]
	s_waitcnt lgkmcnt(1)
	v_mfma_f32_16x16x32_bf16 v[74:77], v[138:141], v[192:195], v[74:77]
	v_mfma_f32_16x16x32_bf16 v[78:81], v[130:133], v[192:195], v[78:81]
	v_mfma_f32_16x16x32_bf16 v[126:129], v[134:137], v[172:175], v[126:129]
	v_mfma_f32_16x16x32_bf16 v[122:125], v[142:145], v[172:175], v[122:125]
	v_mfma_f32_16x16x32_bf16 v[106:109], v[142:145], v[180:183], v[106:109]
	v_mfma_f32_16x16x32_bf16 v[110:113], v[134:137], v[180:183], v[110:113]
	v_mfma_f32_16x16x32_bf16 v[94:97], v[134:137], v[188:191], v[94:97]
	v_mfma_f32_16x16x32_bf16 v[90:93], v[142:145], v[188:191], v[90:93]
	s_waitcnt lgkmcnt(0)
	v_mfma_f32_16x16x32_bf16 v[74:77], v[142:145], v[200:203], v[74:77]
	v_mfma_f32_16x16x32_bf16 v[78:81], v[134:137], v[200:203], v[78:81]
	s_setprio 0
	s_setprio 1
	v_mfma_f32_16x16x32_bf16 v[118:121], v[146:149], v[168:171], v[118:121]
	v_mfma_f32_16x16x32_bf16 v[114:117], v[154:157], v[168:171], v[114:117]
	v_mfma_f32_16x16x32_bf16 v[98:101], v[154:157], v[176:179], v[98:101]
	v_mfma_f32_16x16x32_bf16 v[102:105], v[146:149], v[176:179], v[102:105]
	v_mfma_f32_16x16x32_bf16 v[86:89], v[146:149], v[184:187], v[86:89]
	v_mfma_f32_16x16x32_bf16 v[82:85], v[154:157], v[184:187], v[82:85]
	v_mfma_f32_16x16x32_bf16 v[66:69], v[154:157], v[192:195], v[66:69]
	v_mfma_f32_16x16x32_bf16 v[70:73], v[146:149], v[192:195], v[70:73]
	v_mfma_f32_16x16x32_bf16 v[118:121], v[150:153], v[172:175], v[118:121]
	v_mfma_f32_16x16x32_bf16 v[114:117], v[164:167], v[172:175], v[114:117]
	v_mfma_f32_16x16x32_bf16 v[98:101], v[164:167], v[180:183], v[98:101]
	v_mfma_f32_16x16x32_bf16 v[102:105], v[150:153], v[180:183], v[102:105]
	v_mfma_f32_16x16x32_bf16 v[86:89], v[150:153], v[188:191], v[86:89]
	v_mfma_f32_16x16x32_bf16 v[82:85], v[164:167], v[188:191], v[82:85]
	v_mfma_f32_16x16x32_bf16 v[66:69], v[164:167], v[200:203], v[66:69]
	v_mfma_f32_16x16x32_bf16 v[70:73], v[150:153], v[200:203], v[70:73]
	s_setprio 0
	s_barrier
; #define PG8_STAGE(bufoff, gbase, voff) do { const Src _g = (gbase); _Pragma("unroll") for (int _i = 0; _i < 2; ++_i) \
;         __builtin_amdgcn_raw_ptr_buffer_load_lds(_g.r, (LAS unsigned*)(lds + (bufoff) + ldsw + _i * 8192), 16, (voff)[_i], _g.o, 0, 0); } while (0)
; #define PG8_WAIT_V(n) asm volatile("s_waitcnt vmcnt(" #n ")" ::: "memory")
; template <class Epi, bool ALIGN_EPI, bool SP2, class Hook>
; __device__ __forceinline__ void gemm_phase(LAS unsigned char* lds, const Gemm g, const StaticOrder& S, const Epi& E, Acc& acc, const bool fresh, const Hook& H, const int wave_id) {
;     ...
;         for (int t = t0; t < nt; t += 2) {
;             const bool last = (t == nt - 2);
;             const Src a1 = cA + (size_t)(t + 1) * kstep;
;             const Src a2 = last ? nA : cA + (size_t)(t + 2) * kstep, b2 = last ? nB : cB + (size_t)(t + 2) * kstep;
;             const Src a3 = a2 + kstep, b3 = b2 + kstep;
;             if (last && has_next) H(nxt);
;             if constexpr (SP2) {
;             PG8_TRIP_SP2(PG8_WAIT_V(8));
;             } else {
;             PG8_LDB(B0, 0, 0); PG8_SCHED; PG8_LDA(At, 0, 0); PG8_STAGE(PG8_SA(1, 1), a1 + hstepA, voffA);
;             PG8_WAIT_L(8); PG8_BAR; PG8_WAIT_L(0); PG8_MMA(0, 0, At, B0); PG8_BAR; PG8_SCHED;
;             PG8_LDB(B1, 0, 1); PG8_STAGE(PG8_SB(0, 0), b2, voffB);
;             PG8_BAR; PG8_WAIT_L(0); PG8_MMA(0, 1, At, B1); PG8_BAR;
;             PG8_LDA(At, 0, 1); PG8_STAGE(PG8_SA(0, 0), a2, voffA);
;             PG8_BAR; PG8_WAIT_L(0); PG8_MMA(1, 0, At, B0); PG8_BAR; PG8_SCHED;
;             PG8_STAGE(PG8_SB(0, 1), b2 + hstep, voffB);
;             PG8_WAIT_V(6); PG8_BAR; PG8_MMA(1, 1, At, B1); PG8_BAR;
;             PG8_LDB(B0, 1, 0); PG8_SCHED; PG8_LDA(At, 1, 0); PG8_STAGE(PG8_SA(0, 1), a2 + hstepA, voffA);
;             PG8_WAIT_L(8); PG8_BAR; PG8_WAIT_L(0); PG8_MMA(0, 0, At, B0); PG8_BAR; PG8_SCHED;
;             PG8_LDB(B1, 1, 1); PG8_STAGE(PG8_SB(1, 0), b3, voffB);
;             PG8_BAR; PG8_WAIT_L(0); PG8_MMA(0, 1, At, B1); PG8_BAR;
;             PG8_LDA(At, 1, 1); PG8_STAGE(PG8_SA(1, 0), a3, voffA);
;             PG8_BAR; PG8_WAIT_L(0); PG8_MMA(1, 0, At, B0); PG8_BAR; PG8_SCHED;
;             PG8_STAGE(PG8_SB(1, 1), b3 + hstep, voffB);
;             PG8_WAIT_V(6); PG8_BAR; PG8_MMA(1, 1, At, B1); PG8_BAR;
;             }
;         }
;         if constexpr (ALIGN_EPI) { if (wr == 0) PG8_BAR; }
	s_mov_b32 m0, s39
	s_or_b32 s62, s60, 0x80
	ds_read_b128 v[168:171], v162 offset:49152
	ds_read_b128 v[172:175], v162 offset:50176
	ds_read_b128 v[176:179], v162 offset:51200
	ds_read_b128 v[180:183], v162 offset:52224
	ds_read_b128 v[184:187], v162 offset:53248
	ds_read_b128 v[188:191], v162 offset:54272
	ds_read_b128 v[192:195], v162 offset:55296
	ds_read_b128 v[200:203], v162 offset:56320
	buffer_load_dwordx4 v158, s[16:19], s62 offen lds
	s_mov_b32 m0, s40
	s_add_i32 s60, s60, 0x40080
	buffer_load_dwordx4 v160, s[16:19], s62 offen lds
	s_mov_b32 m0, s43
	s_nop 0
	buffer_load_dwordx4 v158, s[16:19], s60 offen lds
	s_mov_b32 m0, s42
	s_nop 0
	buffer_load_dwordx4 v160, s[16:19], s60 offen lds
	s_mov_b32 m0, s41
	s_nop 0
	buffer_load_dwordx4 v0, s[20:23], s61 offen lds
	s_mov_b32 m0, s33
	s_nop 0
	buffer_load_dwordx4 v159, s[20:23], s61 offen lds
	s_waitcnt vmcnt(8)
	s_waitcnt lgkmcnt(0)
	s_barrier
	s_setprio 1
	s_waitcnt lgkmcnt(7)
	v_mfma_f32_16x16x32_bf16 v[62:65], v[130:133], v[168:171], v[62:65]
	v_mfma_f32_16x16x32_bf16 v[58:61], v[138:141], v[168:171], v[58:61]
	s_waitcnt lgkmcnt(5)
	v_mfma_f32_16x16x32_bf16 v[42:45], v[138:141], v[176:179], v[42:45]
	v_mfma_f32_16x16x32_bf16 v[46:49], v[130:133], v[176:179], v[46:49]
	s_waitcnt lgkmcnt(3)
	v_mfma_f32_16x16x32_bf16 v[30:33], v[130:133], v[184:187], v[30:33]
	v_mfma_f32_16x16x32_bf16 v[26:29], v[138:141], v[184:187], v[26:29]
	s_waitcnt lgkmcnt(1)
	v_mfma_f32_16x16x32_bf16 v[10:13], v[138:141], v[192:195], v[10:13]
	v_mfma_f32_16x16x32_bf16 v[14:17], v[130:133], v[192:195], v[14:17]
	v_mfma_f32_16x16x32_bf16 v[62:65], v[134:137], v[172:175], v[62:65]
	v_mfma_f32_16x16x32_bf16 v[58:61], v[142:145], v[172:175], v[58:61]
	v_mfma_f32_16x16x32_bf16 v[42:45], v[142:145], v[180:183], v[42:45]
	v_mfma_f32_16x16x32_bf16 v[46:49], v[134:137], v[180:183], v[46:49]
	v_mfma_f32_16x16x32_bf16 v[30:33], v[134:137], v[188:191], v[30:33]
	v_mfma_f32_16x16x32_bf16 v[26:29], v[142:145], v[188:191], v[26:29]
	s_waitcnt lgkmcnt(0)
	v_mfma_f32_16x16x32_bf16 v[10:13], v[142:145], v[200:203], v[10:13]
	v_mfma_f32_16x16x32_bf16 v[14:17], v[134:137], v[200:203], v[14:17]
	s_setprio 0
	s_setprio 1
	v_mfma_f32_16x16x32_bf16 v[54:57], v[146:149], v[168:171], v[54:57]
	v_mfma_f32_16x16x32_bf16 v[50:53], v[154:157], v[168:171], v[50:53]
	v_mfma_f32_16x16x32_bf16 v[34:37], v[154:157], v[176:179], v[34:37]
	v_mfma_f32_16x16x32_bf16 v[38:41], v[146:149], v[176:179], v[38:41]
	v_mfma_f32_16x16x32_bf16 v[22:25], v[146:149], v[184:187], v[22:25]
	v_mfma_f32_16x16x32_bf16 v[18:21], v[154:157], v[184:187], v[18:21]
	v_mfma_f32_16x16x32_bf16 v[2:5], v[154:157], v[192:195], v[2:5]
	v_mfma_f32_16x16x32_bf16 v[6:9], v[146:149], v[192:195], v[6:9]
	v_mfma_f32_16x16x32_bf16 v[54:57], v[150:153], v[172:175], v[54:57]
	v_mfma_f32_16x16x32_bf16 v[50:53], v[164:167], v[172:175], v[50:53]
	v_mfma_f32_16x16x32_bf16 v[34:37], v[164:167], v[180:183], v[34:37]
	v_mfma_f32_16x16x32_bf16 v[38:41], v[150:153], v[180:183], v[38:41]
	v_mfma_f32_16x16x32_bf16 v[22:25], v[150:153], v[188:191], v[22:25]
	v_mfma_f32_16x16x32_bf16 v[18:21], v[164:167], v[188:191], v[18:21]
	v_mfma_f32_16x16x32_bf16 v[2:5], v[164:167], v[200:203], v[2:5]
	v_mfma_f32_16x16x32_bf16 v[6:9], v[150:153], v[200:203], v[6:9]
	s_setprio 0
	s_barrier
	s_add_i32 s59, s59, 2
	s_addk_i32 s2, 0x100
	s_addk_i32 s3, 0x100
	s_cmp_gt_u32 s59, 13
	s_cbranch_scc0 .LBB0_1235
	v_readlane_b32 s2, v251, 45
	v_readlane_b32 s3, v251, 46
	s_and_b64 vcc, exec, s[2:3]
	s_cbranch_vccz .LBB0_1238
	s_barrier

.LBB0_1461:
	v_add_u32_e32 v138, 0x10000, v136
	v_add_u32_e32 v139, 0x14000, v136
	ds_read_b128 v[140:143], v138
	ds_read_b128 v[144:147], v138 offset:1024
	ds_read_b128 v[148:151], v138 offset:2048
	ds_read_b128 v[152:155], v138 offset:3072
	ds_read_b128 v[156:159], v139
	ds_read_b128 v[160:163], v139 offset:1024
	ds_read_b128 v[164:167], v139 offset:2048
	ds_read_b128 v[168:171], v139 offset:3072
	s_add_i32 s16, s55, 0xfffc0080
	s_cmp_eq_u32 s54, 12
	s_cselect_b32 s59, s50, s16
	s_cselect_b32 s17, s9, s77
	s_cselect_b32 s16, s8, s76
	s_cselect_b32 s19, s11, s29
	s_cselect_b32 s18, s10, s28
	s_cselect_b32 s57, s51, s56
	s_cselect_b32 s20, s4, s12
	s_cselect_b32 s21, s5, s13
	s_cselect_b32 s22, s6, s14
	s_cselect_b32 s23, s7, s15
	s_or_b32 s58, s59, 0x80
	s_mov_b32 m0, s45
	ds_read_b128 v[172:175], v137
	ds_read_b128 v[176:179], v137 offset:1024
	ds_read_b128 v[180:183], v137 offset:2048
	ds_read_b128 v[184:187], v137 offset:3072
	ds_read_b128 v[188:191], v137 offset:4096
	ds_read_b128 v[192:195], v137 offset:5120
	ds_read_b128 v[200:203], v137 offset:6144
	ds_read_b128 v[204:207], v137 offset:7168
	buffer_load_dwordx4 v132, s[12:15], s55 offen lds
	s_mov_b32 m0, s46
	s_nop 0
	buffer_load_dwordx4 v134, s[12:15], s55 offen lds
	s_waitcnt vmcnt(8)
	s_waitcnt lgkmcnt(0)
	s_barrier
	s_setprio 1
	s_waitcnt lgkmcnt(7)
	v_mfma_f32_16x16x32_bf16 v[124:127], v[140:143], v[172:175], v[124:127]
	v_mfma_f32_16x16x32_bf16 v[116:119], v[148:151], v[172:175], v[116:119]
	s_waitcnt lgkmcnt(5)
	v_mfma_f32_16x16x32_bf16 v[100:103], v[148:151], v[180:183], v[100:103]
	v_mfma_f32_16x16x32_bf16 v[108:111], v[140:143], v[180:183], v[108:111]
	s_waitcnt lgkmcnt(3)
	v_mfma_f32_16x16x32_bf16 v[92:95], v[140:143], v[188:191], v[92:95]
	v_mfma_f32_16x16x32_bf16 v[84:87], v[148:151], v[188:191], v[84:87]
	s_waitcnt lgkmcnt(1)
	v_mfma_f32_16x16x32_bf16 v[64:67], v[148:151], v[200:203], v[64:67]
	v_mfma_f32_16x16x32_bf16 v[76:79], v[140:143], v[200:203], v[76:79]
	v_mfma_f32_16x16x32_bf16 v[124:127], v[144:147], v[176:179], v[124:127]
	v_mfma_f32_16x16x32_bf16 v[116:119], v[152:155], v[176:179], v[116:119]
	v_mfma_f32_16x16x32_bf16 v[100:103], v[152:155], v[184:187], v[100:103]
	v_mfma_f32_16x16x32_bf16 v[108:111], v[144:147], v[184:187], v[108:111]
	v_mfma_f32_16x16x32_bf16 v[92:95], v[144:147], v[192:195], v[92:95]
	v_mfma_f32_16x16x32_bf16 v[84:87], v[152:155], v[192:195], v[84:87]
	s_waitcnt lgkmcnt(0)
	v_mfma_f32_16x16x32_bf16 v[64:67], v[152:155], v[204:207], v[64:67]
	v_mfma_f32_16x16x32_bf16 v[76:79], v[144:147], v[204:207], v[76:79]
	s_setprio 0
	s_setprio 1
	v_mfma_f32_16x16x32_bf16 v[128:131], v[156:159], v[172:175], v[128:131]
	v_mfma_f32_16x16x32_bf16 v[120:123], v[164:167], v[172:175], v[120:123]
	v_mfma_f32_16x16x32_bf16 v[104:107], v[164:167], v[180:183], v[104:107]
	v_mfma_f32_16x16x32_bf16 v[112:115], v[156:159], v[180:183], v[112:115]
	v_mfma_f32_16x16x32_bf16 v[96:99], v[156:159], v[188:191], v[96:99]
	v_mfma_f32_16x16x32_bf16 v[88:91], v[164:167], v[188:191], v[88:91]
	v_mfma_f32_16x16x32_bf16 v[68:71], v[164:167], v[200:203], v[68:71]
	v_mfma_f32_16x16x32_bf16 v[80:83], v[156:159], v[200:203], v[80:83]
	v_mfma_f32_16x16x32_bf16 v[128:131], v[160:163], v[176:179], v[128:131]
	v_mfma_f32_16x16x32_bf16 v[120:123], v[168:171], v[176:179], v[120:123]
	v_mfma_f32_16x16x32_bf16 v[104:107], v[168:171], v[184:187], v[104:107]
	v_mfma_f32_16x16x32_bf16 v[112:115], v[160:163], v[184:187], v[112:115]
	v_mfma_f32_16x16x32_bf16 v[96:99], v[160:163], v[192:195], v[96:99]
	v_mfma_f32_16x16x32_bf16 v[88:91], v[168:171], v[192:195], v[88:91]
	v_mfma_f32_16x16x32_bf16 v[68:71], v[168:171], v[204:207], v[68:71]
	v_mfma_f32_16x16x32_bf16 v[80:83], v[160:163], v[204:207], v[80:83]
	s_setprio 0
	s_barrier
	s_mov_b32 m0, s92
	ds_read_b128 v[172:175], v137 offset:16384
	ds_read_b128 v[176:179], v137 offset:17408
	ds_read_b128 v[180:183], v137 offset:18432
	ds_read_b128 v[184:187], v137 offset:19456
	ds_read_b128 v[188:191], v137 offset:20480
	ds_read_b128 v[192:195], v137 offset:21504
	ds_read_b128 v[200:203], v137 offset:22528
	ds_read_b128 v[204:207], v137 offset:23552
	buffer_load_dwordx4 v133, s[16:19], s57 offen lds
	s_mov_b32 m0, s93
	s_add_i32 s60, s57, 0x40000
	buffer_load_dwordx4 v135, s[16:19], s57 offen lds
	s_mov_b32 m0, s94
	s_nop 0
	buffer_load_dwordx4 v133, s[16:19], s60 offen lds
	s_mov_b32 m0, s95
	s_nop 0
	buffer_load_dwordx4 v135, s[16:19], s60 offen lds
	s_mov_b32 m0, s44
	s_nop 0
	buffer_load_dwordx4 v132, s[20:23], s59 offen lds
	s_mov_b32 m0, s36
	s_nop 0
	buffer_load_dwordx4 v134, s[20:23], s59 offen lds
	s_waitcnt vmcnt(8)
	s_waitcnt lgkmcnt(0)
	s_barrier
; #define PG8_WAIT_V(n) asm volatile("s_waitcnt vmcnt(" #n ")" ::: "memory")
; template <class Epi, bool ALIGN_EPI, bool SP2, class Hook>
; __device__ __forceinline__ void gemm_phase(LAS unsigned char* lds, const Gemm g, const StaticOrder& S, const Epi& E, Acc& acc, const bool fresh, const Hook& H, const int wave_id) {
;     ...
;         for (int t = t0; t < nt; t += 2) {
;             const bool last = (t == nt - 2);
;             const Src a1 = cA + (size_t)(t + 1) * kstep;
;             const Src a2 = last ? nA : cA + (size_t)(t + 2) * kstep, b2 = last ? nB : cB + (size_t)(t + 2) * kstep;
;             const Src a3 = a2 + kstep, b3 = b2 + kstep;
;             if (last && has_next) H(nxt);
;             if constexpr (SP2) {
;             PG8_TRIP_SP2(PG8_WAIT_V(8));
	s_setprio 1
	s_waitcnt lgkmcnt(7)
	v_mfma_f32_16x16x32_bf16 v[60:63], v[140:143], v[172:175], v[60:63]
	v_mfma_f32_16x16x32_bf16 v[52:55], v[148:151], v[172:175], v[52:55]
	s_waitcnt lgkmcnt(5)
	v_mfma_f32_16x16x32_bf16 v[36:39], v[148:151], v[180:183], v[36:39]
	v_mfma_f32_16x16x32_bf16 v[44:47], v[140:143], v[180:183], v[44:47]
	s_waitcnt lgkmcnt(3)
	v_mfma_f32_16x16x32_bf16 v[28:31], v[140:143], v[188:191], v[28:31]
	v_mfma_f32_16x16x32_bf16 v[20:23], v[148:151], v[188:191], v[20:23]
	s_waitcnt lgkmcnt(1)
	v_mfma_f32_16x16x32_bf16 v[2:5], v[148:151], v[200:203], v[4:7]
	v_mfma_f32_16x16x32_bf16 v[12:15], v[140:143], v[200:203], v[12:15]
	v_mfma_f32_16x16x32_bf16 v[60:63], v[144:147], v[176:179], v[60:63]
	v_mfma_f32_16x16x32_bf16 v[52:55], v[152:155], v[176:179], v[52:55]
	v_mfma_f32_16x16x32_bf16 v[36:39], v[152:155], v[184:187], v[36:39]
	v_mfma_f32_16x16x32_bf16 v[44:47], v[144:147], v[184:187], v[44:47]
	v_mfma_f32_16x16x32_bf16 v[28:31], v[144:147], v[192:195], v[28:31]
	v_mfma_f32_16x16x32_bf16 v[20:23], v[152:155], v[192:195], v[20:23]
	s_waitcnt lgkmcnt(0)
	v_mfma_f32_16x16x32_bf16 v[2:5], v[152:155], v[204:207], v[2:5]
	v_mfma_f32_16x16x32_bf16 v[12:15], v[144:147], v[204:207], v[12:15]
	s_setprio 0
	s_setprio 1
	v_mfma_f32_16x16x32_bf16 v[72:75], v[156:159], v[172:175], v[72:75]
	v_mfma_f32_16x16x32_bf16 v[56:59], v[164:167], v[172:175], v[56:59]
	v_mfma_f32_16x16x32_bf16 v[40:43], v[164:167], v[180:183], v[40:43]
	v_mfma_f32_16x16x32_bf16 v[48:51], v[156:159], v[180:183], v[48:51]
	v_mfma_f32_16x16x32_bf16 v[32:35], v[156:159], v[188:191], v[32:35]
	v_mfma_f32_16x16x32_bf16 v[24:27], v[164:167], v[188:191], v[24:27]
	v_mfma_f32_16x16x32_bf16 v[6:9], v[164:167], v[200:203], v[8:11]
	v_mfma_f32_16x16x32_bf16 v[16:19], v[156:159], v[200:203], v[16:19]
	v_mfma_f32_16x16x32_bf16 v[72:75], v[160:163], v[176:179], v[72:75]
	v_mfma_f32_16x16x32_bf16 v[56:59], v[168:171], v[176:179], v[56:59]
	v_mfma_f32_16x16x32_bf16 v[40:43], v[168:171], v[184:187], v[40:43]
	v_mfma_f32_16x16x32_bf16 v[48:51], v[160:163], v[184:187], v[48:51]
	v_mfma_f32_16x16x32_bf16 v[32:35], v[160:163], v[192:195], v[32:35]
	v_mfma_f32_16x16x32_bf16 v[24:27], v[168:171], v[192:195], v[24:27]
	v_mfma_f32_16x16x32_bf16 v[8:11], v[168:171], v[204:207], v[6:9]
	v_mfma_f32_16x16x32_bf16 v[16:19], v[160:163], v[204:207], v[16:19]
	s_setprio 0
	s_barrier
	v_add_u32_e32 v140, 0x18000, v136
	v_add_u32_e32 v141, 0x1c000, v136
	ds_read_b128 v[142:145], v140
	ds_read_b128 v[146:149], v140 offset:1024
	ds_read_b128 v[150:153], v140 offset:2048
	ds_read_b128 v[154:157], v140 offset:3072
	ds_read_b128 v[158:161], v141
	ds_read_b128 v[162:165], v141 offset:1024
	ds_read_b128 v[166:169], v141 offset:2048
	ds_read_b128 v[170:173], v141 offset:3072
	s_add_i32 s59, s59, 0x40000
	s_mov_b32 m0, s37
	ds_read_b128 v[174:177], v137 offset:32768
	ds_read_b128 v[178:181], v137 offset:33792
	ds_read_b128 v[182:185], v137 offset:34816
	ds_read_b128 v[186:189], v137 offset:35840
	ds_read_b128 v[190:193], v137 offset:36864
	ds_read_b128 v[194:197], v137 offset:37888
	ds_read_b128 v[200:203], v137 offset:38912
	ds_read_b128 v[204:207], v137 offset:39936
	buffer_load_dwordx4 v132, s[20:23], s59 offen lds
	s_mov_b32 m0, s38
	s_nop 0
	buffer_load_dwordx4 v134, s[20:23], s59 offen lds
	s_waitcnt vmcnt(8)
	s_waitcnt lgkmcnt(0)
	s_barrier
	s_setprio 1
	s_waitcnt lgkmcnt(7)
	v_mfma_f32_16x16x32_bf16 v[124:127], v[142:145], v[174:177], v[124:127]
	v_mfma_f32_16x16x32_bf16 v[116:119], v[150:153], v[174:177], v[116:119]
	s_waitcnt lgkmcnt(5)
	v_mfma_f32_16x16x32_bf16 v[100:103], v[150:153], v[182:185], v[100:103]
	v_mfma_f32_16x16x32_bf16 v[108:111], v[142:145], v[182:185], v[108:111]
	s_waitcnt lgkmcnt(3)
	v_mfma_f32_16x16x32_bf16 v[92:95], v[142:145], v[190:193], v[92:95]
	v_mfma_f32_16x16x32_bf16 v[84:87], v[150:153], v[190:193], v[84:87]
	s_waitcnt lgkmcnt(1)
	v_mfma_f32_16x16x32_bf16 v[64:67], v[150:153], v[200:203], v[64:67]
	v_mfma_f32_16x16x32_bf16 v[76:79], v[142:145], v[200:203], v[76:79]
	v_mfma_f32_16x16x32_bf16 v[124:127], v[146:149], v[178:181], v[124:127]
	v_mfma_f32_16x16x32_bf16 v[116:119], v[154:157], v[178:181], v[116:119]
	v_mfma_f32_16x16x32_bf16 v[100:103], v[154:157], v[186:189], v[100:103]
	v_mfma_f32_16x16x32_bf16 v[108:111], v[146:149], v[186:189], v[108:111]
	v_mfma_f32_16x16x32_bf16 v[92:95], v[146:149], v[194:197], v[92:95]
	v_mfma_f32_16x16x32_bf16 v[84:87], v[154:157], v[194:197], v[84:87]
	s_waitcnt lgkmcnt(0)
	v_mfma_f32_16x16x32_bf16 v[64:67], v[154:157], v[204:207], v[64:67]
	v_mfma_f32_16x16x32_bf16 v[76:79], v[146:149], v[204:207], v[76:79]
	s_setprio 0
	s_setprio 1
	v_mfma_f32_16x16x32_bf16 v[128:131], v[158:161], v[174:177], v[128:131]
	v_mfma_f32_16x16x32_bf16 v[120:123], v[166:169], v[174:177], v[120:123]
	v_mfma_f32_16x16x32_bf16 v[104:107], v[166:169], v[182:185], v[104:107]
	v_mfma_f32_16x16x32_bf16 v[112:115], v[158:161], v[182:185], v[112:115]
	v_mfma_f32_16x16x32_bf16 v[96:99], v[158:161], v[190:193], v[96:99]
	v_mfma_f32_16x16x32_bf16 v[88:91], v[166:169], v[190:193], v[88:91]
	v_mfma_f32_16x16x32_bf16 v[68:71], v[166:169], v[200:203], v[68:71]
	v_mfma_f32_16x16x32_bf16 v[80:83], v[158:161], v[200:203], v[80:83]
	v_mfma_f32_16x16x32_bf16 v[128:131], v[162:165], v[178:181], v[128:131]
	v_mfma_f32_16x16x32_bf16 v[120:123], v[170:173], v[178:181], v[120:123]
	v_mfma_f32_16x16x32_bf16 v[104:107], v[170:173], v[186:189], v[104:107]
	v_mfma_f32_16x16x32_bf16 v[112:115], v[162:165], v[186:189], v[112:115]
	v_mfma_f32_16x16x32_bf16 v[96:99], v[162:165], v[194:197], v[96:99]
	v_mfma_f32_16x16x32_bf16 v[88:91], v[170:173], v[194:197], v[88:91]
	v_mfma_f32_16x16x32_bf16 v[68:71], v[170:173], v[204:207], v[68:71]
	v_mfma_f32_16x16x32_bf16 v[80:83], v[162:165], v[204:207], v[80:83]
	s_setprio 0
	s_barrier
; #define PG8_WAIT_V(n) asm volatile("s_waitcnt vmcnt(" #n ")" ::: "memory")
; template <class Epi, bool ALIGN_EPI, bool SP2, class Hook>
; __device__ __forceinline__ void gemm_phase(LAS unsigned char* lds, const Gemm g, const StaticOrder& S, const Epi& E, Acc& acc, const bool fresh, const Hook& H, const int wave_id) {
;     ...
;         for (int t = t0; t < nt; t += 2) {
;             const bool last = (t == nt - 2);
;             const Src a1 = cA + (size_t)(t + 1) * kstep;
;             const Src a2 = last ? nA : cA + (size_t)(t + 2) * kstep, b2 = last ? nB : cB + (size_t)(t + 2) * kstep;
;             const Src a3 = a2 + kstep, b3 = b2 + kstep;
;             if (last && has_next) H(nxt);
;             if constexpr (SP2) {
;             PG8_TRIP_SP2(PG8_WAIT_V(8));
	s_mov_b32 m0, s39
	s_or_b32 s59, s57, 0x80
	ds_read_b128 v[174:177], v137 offset:49152
	ds_read_b128 v[178:181], v137 offset:50176
	ds_read_b128 v[182:185], v137 offset:51200
	ds_read_b128 v[186:189], v137 offset:52224
	ds_read_b128 v[190:193], v137 offset:53248
	ds_read_b128 v[194:197], v137 offset:54272
	ds_read_b128 v[200:203], v137 offset:55296
	ds_read_b128 v[204:207], v137 offset:56320
	buffer_load_dwordx4 v133, s[16:19], s59 offen lds
	s_mov_b32 m0, s40
	s_add_i32 s57, s57, 0x40080
	buffer_load_dwordx4 v135, s[16:19], s59 offen lds
	s_mov_b32 m0, s43
	s_nop 0
	buffer_load_dwordx4 v133, s[16:19], s57 offen lds
	s_mov_b32 m0, s42
	s_nop 0
	buffer_load_dwordx4 v135, s[16:19], s57 offen lds
	s_mov_b32 m0, s41
	s_nop 0
	buffer_load_dwordx4 v132, s[20:23], s58 offen lds
	s_mov_b32 m0, s33
	s_nop 0
	buffer_load_dwordx4 v134, s[20:23], s58 offen lds
	s_waitcnt vmcnt(8)
	s_waitcnt lgkmcnt(0)
	s_barrier
	s_setprio 1
	s_waitcnt lgkmcnt(7)
	v_mfma_f32_16x16x32_bf16 v[60:63], v[142:145], v[174:177], v[60:63]
	v_mfma_f32_16x16x32_bf16 v[52:55], v[150:153], v[174:177], v[52:55]
	s_waitcnt lgkmcnt(5)
	v_mfma_f32_16x16x32_bf16 v[36:39], v[150:153], v[182:185], v[36:39]
	v_mfma_f32_16x16x32_bf16 v[44:47], v[142:145], v[182:185], v[44:47]
	s_waitcnt lgkmcnt(3)
	v_mfma_f32_16x16x32_bf16 v[28:31], v[142:145], v[190:193], v[28:31]
	v_mfma_f32_16x16x32_bf16 v[20:23], v[150:153], v[190:193], v[20:23]
	s_waitcnt lgkmcnt(1)
	v_mfma_f32_16x16x32_bf16 v[2:5], v[150:153], v[200:203], v[2:5]
	v_mfma_f32_16x16x32_bf16 v[12:15], v[142:145], v[200:203], v[12:15]
	v_mfma_f32_16x16x32_bf16 v[60:63], v[146:149], v[178:181], v[60:63]
	v_mfma_f32_16x16x32_bf16 v[52:55], v[154:157], v[178:181], v[52:55]
	v_mfma_f32_16x16x32_bf16 v[36:39], v[154:157], v[186:189], v[36:39]
	v_mfma_f32_16x16x32_bf16 v[44:47], v[146:149], v[186:189], v[44:47]
	v_mfma_f32_16x16x32_bf16 v[28:31], v[146:149], v[194:197], v[28:31]
	v_mfma_f32_16x16x32_bf16 v[20:23], v[154:157], v[194:197], v[20:23]
	s_waitcnt lgkmcnt(0)
	v_mfma_f32_16x16x32_bf16 v[4:7], v[154:157], v[204:207], v[2:5]
	v_mfma_f32_16x16x32_bf16 v[12:15], v[146:149], v[204:207], v[12:15]
	s_setprio 0
	s_setprio 1
	v_mfma_f32_16x16x32_bf16 v[72:75], v[158:161], v[174:177], v[72:75]
	v_mfma_f32_16x16x32_bf16 v[56:59], v[166:169], v[174:177], v[56:59]
	v_mfma_f32_16x16x32_bf16 v[40:43], v[166:169], v[182:185], v[40:43]
	v_mfma_f32_16x16x32_bf16 v[48:51], v[158:161], v[182:185], v[48:51]
	v_mfma_f32_16x16x32_bf16 v[32:35], v[158:161], v[190:193], v[32:35]
	v_mfma_f32_16x16x32_bf16 v[24:27], v[166:169], v[190:193], v[24:27]
	v_mfma_f32_16x16x32_bf16 v[8:11], v[166:169], v[200:203], v[8:11]
	v_mfma_f32_16x16x32_bf16 v[16:19], v[158:161], v[200:203], v[16:19]
	v_mfma_f32_16x16x32_bf16 v[72:75], v[162:165], v[178:181], v[72:75]
	v_mfma_f32_16x16x32_bf16 v[56:59], v[170:173], v[178:181], v[56:59]
	v_mfma_f32_16x16x32_bf16 v[40:43], v[170:173], v[186:189], v[40:43]
	v_mfma_f32_16x16x32_bf16 v[48:51], v[162:165], v[186:189], v[48:51]
	v_mfma_f32_16x16x32_bf16 v[32:35], v[162:165], v[194:197], v[32:35]
	v_mfma_f32_16x16x32_bf16 v[24:27], v[170:173], v[194:197], v[24:27]
	v_mfma_f32_16x16x32_bf16 v[8:11], v[170:173], v[204:207], v[8:11]
	v_mfma_f32_16x16x32_bf16 v[16:19], v[162:165], v[204:207], v[16:19]
	s_setprio 0
	s_barrier
	s_add_i32 s54, s54, 2
	s_addk_i32 s55, 0x100
	s_addk_i32 s56, 0x100
	s_cmp_gt_u32 s54, 13
	s_cbranch_scc0 .LBB0_1461
	v_readlane_b32 s12, v251, 45
	v_readlane_b32 s13, v251, 46
	s_and_b64 vcc, exec, s[12:13]
	s_cbranch_vccz .LBB0_1464
	s_barrier

; #define PG8_WAIT_V(n) asm volatile("s_waitcnt vmcnt(" #n ")" ::: "memory")
; template <class Epi, bool ALIGN_EPI, bool SP2, class Hook>
; __device__ __forceinline__ void gemm_phase(LAS unsigned char* lds, const Gemm g, const StaticOrder& S, const Epi& E, Acc& acc, const bool fresh, const Hook& H, const int wave_id) {
;     ...
;         for (int t = t0; t < nt; t += 2) {
;             const bool last = (t == nt - 2);
;             const Src a1 = cA + (size_t)(t + 1) * kstep;
;             const Src a2 = last ? nA : cA + (size_t)(t + 2) * kstep, b2 = last ? nB : cB + (size_t)(t + 2) * kstep;
;             const Src a3 = a2 + kstep, b3 = b2 + kstep;
;             if (last && has_next) H(nxt);
;             if constexpr (SP2) {
;             PG8_TRIP_SP2(PG8_WAIT_V(8));
.LBB0_1572:
	v_add_u32_e32 v142, 0x10000, v161
	v_add_u32_e32 v163, 0x14000, v161
	ds_read_b128 v[130:133], v142
	ds_read_b128 v[134:137], v142 offset:1024
	ds_read_b128 v[138:141], v142 offset:2048
	ds_read_b128 v[142:145], v142 offset:3072
	ds_read_b128 v[146:149], v163
	ds_read_b128 v[150:153], v163 offset:1024
	ds_read_b128 v[154:157], v163 offset:2048
	ds_read_b128 v[164:167], v163 offset:3072
	s_add_i32 s16, s2, 0xfff40080
	s_cmp_eq_u32 s61, 40
	s_cselect_b32 s64, s57, s16
	s_cselect_b32 s17, s35, s9
	s_cselect_b32 s16, s34, s8
	s_cselect_b32 s19, s51, s53
	s_cselect_b32 s18, s50, s52
	s_cselect_b32 s62, s58, s3
	s_cselect_b32 s20, s10, s12
	s_cselect_b32 s21, s11, s13
	s_cselect_b32 s22, s30, s14
	s_cselect_b32 s23, s31, s15
	s_or_b32 s63, s64, 0x80
	s_mov_b32 m0, s45
	ds_read_b128 v[168:171], v162
	ds_read_b128 v[172:175], v162 offset:1024
	ds_read_b128 v[176:179], v162 offset:2048
	ds_read_b128 v[180:183], v162 offset:3072
	ds_read_b128 v[184:187], v162 offset:4096
	ds_read_b128 v[188:191], v162 offset:5120
	ds_read_b128 v[192:195], v162 offset:6144
	ds_read_b128 v[200:203], v162 offset:7168
	buffer_load_dwordx4 v0, s[12:15], s2 offen lds
	s_mov_b32 m0, s46
	s_nop 0
	buffer_load_dwordx4 v159, s[12:15], s2 offen lds
	s_waitcnt vmcnt(8)
	s_waitcnt lgkmcnt(0)
	s_barrier
	s_setprio 1
	s_waitcnt lgkmcnt(7)
	v_mfma_f32_16x16x32_bf16 v[126:129], v[130:133], v[168:171], v[126:129]
	v_mfma_f32_16x16x32_bf16 v[122:125], v[138:141], v[168:171], v[122:125]
	s_waitcnt lgkmcnt(5)
	v_mfma_f32_16x16x32_bf16 v[106:109], v[138:141], v[176:179], v[106:109]
	v_mfma_f32_16x16x32_bf16 v[110:113], v[130:133], v[176:179], v[110:113]
	s_waitcnt lgkmcnt(3)
	v_mfma_f32_16x16x32_bf16 v[94:97], v[130:133], v[184:187], v[94:97]
	v_mfma_f32_16x16x32_bf16 v[90:93], v[138:141], v[184:187], v[90:93]
	s_waitcnt lgkmcnt(1)
	v_mfma_f32_16x16x32_bf16 v[74:77], v[138:141], v[192:195], v[74:77]
	v_mfma_f32_16x16x32_bf16 v[78:81], v[130:133], v[192:195], v[78:81]
	v_mfma_f32_16x16x32_bf16 v[126:129], v[134:137], v[172:175], v[126:129]
	v_mfma_f32_16x16x32_bf16 v[122:125], v[142:145], v[172:175], v[122:125]
	v_mfma_f32_16x16x32_bf16 v[106:109], v[142:145], v[180:183], v[106:109]
	v_mfma_f32_16x16x32_bf16 v[110:113], v[134:137], v[180:183], v[110:113]
	v_mfma_f32_16x16x32_bf16 v[94:97], v[134:137], v[188:191], v[94:97]
	v_mfma_f32_16x16x32_bf16 v[90:93], v[142:145], v[188:191], v[90:93]
	s_waitcnt lgkmcnt(0)
	v_mfma_f32_16x16x32_bf16 v[74:77], v[142:145], v[200:203], v[74:77]
	v_mfma_f32_16x16x32_bf16 v[78:81], v[134:137], v[200:203], v[78:81]
	s_setprio 0
	s_setprio 1
	v_mfma_f32_16x16x32_bf16 v[118:121], v[146:149], v[168:171], v[118:121]
	v_mfma_f32_16x16x32_bf16 v[114:117], v[154:157], v[168:171], v[114:117]
	v_mfma_f32_16x16x32_bf16 v[98:101], v[154:157], v[176:179], v[98:101]
	v_mfma_f32_16x16x32_bf16 v[102:105], v[146:149], v[176:179], v[102:105]
	v_mfma_f32_16x16x32_bf16 v[86:89], v[146:149], v[184:187], v[86:89]
	v_mfma_f32_16x16x32_bf16 v[82:85], v[154:157], v[184:187], v[82:85]
	v_mfma_f32_16x16x32_bf16 v[66:69], v[154:157], v[192:195], v[66:69]
	v_mfma_f32_16x16x32_bf16 v[70:73], v[146:149], v[192:195], v[70:73]
	v_mfma_f32_16x16x32_bf16 v[118:121], v[150:153], v[172:175], v[118:121]
	v_mfma_f32_16x16x32_bf16 v[114:117], v[164:167], v[172:175], v[114:117]
	v_mfma_f32_16x16x32_bf16 v[98:101], v[164:167], v[180:183], v[98:101]
	v_mfma_f32_16x16x32_bf16 v[102:105], v[150:153], v[180:183], v[102:105]
	v_mfma_f32_16x16x32_bf16 v[86:89], v[150:153], v[188:191], v[86:89]
	v_mfma_f32_16x16x32_bf16 v[82:85], v[164:167], v[188:191], v[82:85]
	v_mfma_f32_16x16x32_bf16 v[66:69], v[164:167], v[200:203], v[66:69]
	v_mfma_f32_16x16x32_bf16 v[70:73], v[150:153], v[200:203], v[70:73]
	s_setprio 0
	s_barrier
	s_mov_b32 m0, s92
	ds_read_b128 v[168:171], v162 offset:16384
	ds_read_b128 v[172:175], v162 offset:17408
	ds_read_b128 v[176:179], v162 offset:18432
	ds_read_b128 v[180:183], v162 offset:19456
	ds_read_b128 v[184:187], v162 offset:20480
	ds_read_b128 v[188:191], v162 offset:21504
	ds_read_b128 v[192:195], v162 offset:22528
	ds_read_b128 v[200:203], v162 offset:23552
	buffer_load_dwordx4 v158, s[16:19], s62 offen lds
	s_mov_b32 m0, s93
	s_add_i32 s65, s62, 0xb0000
	buffer_load_dwordx4 v160, s[16:19], s62 offen lds
	s_mov_b32 m0, s94
	s_nop 0
	buffer_load_dwordx4 v158, s[16:19], s65 offen lds
	s_mov_b32 m0, s95
	s_nop 0
	buffer_load_dwordx4 v160, s[16:19], s65 offen lds
	s_mov_b32 m0, s44
	s_nop 0
	buffer_load_dwordx4 v0, s[20:23], s64 offen lds
	s_mov_b32 m0, s36
	s_nop 0
	buffer_load_dwordx4 v159, s[20:23], s64 offen lds
	s_waitcnt vmcnt(8)
	s_waitcnt lgkmcnt(0)
	s_barrier
; #define PG8_WAIT_V(n) asm volatile("s_waitcnt vmcnt(" #n ")" ::: "memory")
; template <class Epi, bool ALIGN_EPI, bool SP2, class Hook>
; __device__ __forceinline__ void gemm_phase(LAS unsigned char* lds, const Gemm g, const StaticOrder& S, const Epi& E, Acc& acc, const bool fresh, const Hook& H, const int wave_id) {
;     ...
;         for (int t = t0; t < nt; t += 2) {
;             const bool last = (t == nt - 2);
;             const Src a1 = cA + (size_t)(t + 1) * kstep;
;             const Src a2 = last ? nA : cA + (size_t)(t + 2) * kstep, b2 = last ? nB : cB + (size_t)(t + 2) * kstep;
;             const Src a3 = a2 + kstep, b3 = b2 + kstep;
;             if (last && has_next) H(nxt);
;             if constexpr (SP2) {
;             PG8_TRIP_SP2(PG8_WAIT_V(8));
	s_setprio 1
	s_waitcnt lgkmcnt(7)
	v_mfma_f32_16x16x32_bf16 v[62:65], v[130:133], v[168:171], v[62:65]
	v_mfma_f32_16x16x32_bf16 v[58:61], v[138:141], v[168:171], v[58:61]
	s_waitcnt lgkmcnt(5)
	v_mfma_f32_16x16x32_bf16 v[42:45], v[138:141], v[176:179], v[42:45]
	v_mfma_f32_16x16x32_bf16 v[46:49], v[130:133], v[176:179], v[46:49]
	s_waitcnt lgkmcnt(3)
	v_mfma_f32_16x16x32_bf16 v[30:33], v[130:133], v[184:187], v[30:33]
	v_mfma_f32_16x16x32_bf16 v[26:29], v[138:141], v[184:187], v[26:29]
	s_waitcnt lgkmcnt(1)
	v_mfma_f32_16x16x32_bf16 v[10:13], v[138:141], v[192:195], v[10:13]
	v_mfma_f32_16x16x32_bf16 v[14:17], v[130:133], v[192:195], v[14:17]
	v_mfma_f32_16x16x32_bf16 v[62:65], v[134:137], v[172:175], v[62:65]
	v_mfma_f32_16x16x32_bf16 v[58:61], v[142:145], v[172:175], v[58:61]
	v_mfma_f32_16x16x32_bf16 v[42:45], v[142:145], v[180:183], v[42:45]
	v_mfma_f32_16x16x32_bf16 v[46:49], v[134:137], v[180:183], v[46:49]
	v_mfma_f32_16x16x32_bf16 v[30:33], v[134:137], v[188:191], v[30:33]
	v_mfma_f32_16x16x32_bf16 v[26:29], v[142:145], v[188:191], v[26:29]
	s_waitcnt lgkmcnt(0)
	v_mfma_f32_16x16x32_bf16 v[10:13], v[142:145], v[200:203], v[10:13]
	v_mfma_f32_16x16x32_bf16 v[14:17], v[134:137], v[200:203], v[14:17]
	s_setprio 0
	s_setprio 1
	v_mfma_f32_16x16x32_bf16 v[54:57], v[146:149], v[168:171], v[54:57]
	v_mfma_f32_16x16x32_bf16 v[50:53], v[154:157], v[168:171], v[50:53]
	v_mfma_f32_16x16x32_bf16 v[34:37], v[154:157], v[176:179], v[34:37]
	v_mfma_f32_16x16x32_bf16 v[38:41], v[146:149], v[176:179], v[38:41]
	v_mfma_f32_16x16x32_bf16 v[22:25], v[146:149], v[184:187], v[22:25]
	v_mfma_f32_16x16x32_bf16 v[18:21], v[154:157], v[184:187], v[18:21]
	v_mfma_f32_16x16x32_bf16 v[2:5], v[154:157], v[192:195], v[2:5]
	v_mfma_f32_16x16x32_bf16 v[6:9], v[146:149], v[192:195], v[6:9]
	v_mfma_f32_16x16x32_bf16 v[54:57], v[150:153], v[172:175], v[54:57]
	v_mfma_f32_16x16x32_bf16 v[50:53], v[164:167], v[172:175], v[50:53]
	v_mfma_f32_16x16x32_bf16 v[34:37], v[164:167], v[180:183], v[34:37]
	v_mfma_f32_16x16x32_bf16 v[38:41], v[150:153], v[180:183], v[38:41]
	v_mfma_f32_16x16x32_bf16 v[22:25], v[150:153], v[188:191], v[22:25]
	v_mfma_f32_16x16x32_bf16 v[18:21], v[164:167], v[188:191], v[18:21]
	v_mfma_f32_16x16x32_bf16 v[2:5], v[164:167], v[200:203], v[2:5]
	v_mfma_f32_16x16x32_bf16 v[6:9], v[150:153], v[200:203], v[6:9]
	s_setprio 0
	s_barrier
	v_add_u32_e32 v142, 0x18000, v161
	v_add_u32_e32 v163, 0x1c000, v161
	ds_read_b128 v[130:133], v142
	ds_read_b128 v[134:137], v142 offset:1024
	ds_read_b128 v[138:141], v142 offset:2048
	ds_read_b128 v[142:145], v142 offset:3072
	ds_read_b128 v[146:149], v163
	ds_read_b128 v[150:153], v163 offset:1024
	ds_read_b128 v[154:157], v163 offset:2048
	ds_read_b128 v[164:167], v163 offset:3072
	s_add_i32 s64, s64, 0xc0000
	s_mov_b32 m0, s37
	ds_read_b128 v[168:171], v162 offset:32768
	ds_read_b128 v[172:175], v162 offset:33792
	ds_read_b128 v[176:179], v162 offset:34816
	ds_read_b128 v[180:183], v162 offset:35840
	ds_read_b128 v[184:187], v162 offset:36864
	ds_read_b128 v[188:191], v162 offset:37888
	ds_read_b128 v[192:195], v162 offset:38912
	ds_read_b128 v[200:203], v162 offset:39936
	buffer_load_dwordx4 v0, s[20:23], s64 offen lds
	s_mov_b32 m0, s38
	s_nop 0
	buffer_load_dwordx4 v159, s[20:23], s64 offen lds
	s_waitcnt vmcnt(8)
	s_waitcnt lgkmcnt(0)
	s_barrier
	s_setprio 1
	s_waitcnt lgkmcnt(7)
	v_mfma_f32_16x16x32_bf16 v[126:129], v[130:133], v[168:171], v[126:129]
	v_mfma_f32_16x16x32_bf16 v[122:125], v[138:141], v[168:171], v[122:125]
	s_waitcnt lgkmcnt(5)
	v_mfma_f32_16x16x32_bf16 v[106:109], v[138:141], v[176:179], v[106:109]
	v_mfma_f32_16x16x32_bf16 v[110:113], v[130:133], v[176:179], v[110:113]
	s_waitcnt lgkmcnt(3)
	v_mfma_f32_16x16x32_bf16 v[94:97], v[130:133], v[184:187], v[94:97]
	v_mfma_f32_16x16x32_bf16 v[90:93], v[138:141], v[184:187], v[90:93]
	s_waitcnt lgkmcnt(1)
	v_mfma_f32_16x16x32_bf16 v[74:77], v[138:141], v[192:195], v[74:77]
	v_mfma_f32_16x16x32_bf16 v[78:81], v[130:133], v[192:195], v[78:81]
	v_mfma_f32_16x16x32_bf16 v[126:129], v[134:137], v[172:175], v[126:129]
	v_mfma_f32_16x16x32_bf16 v[122:125], v[142:145], v[172:175], v[122:125]
	v_mfma_f32_16x16x32_bf16 v[106:109], v[142:145], v[180:183], v[106:109]
	v_mfma_f32_16x16x32_bf16 v[110:113], v[134:137], v[180:183], v[110:113]
	v_mfma_f32_16x16x32_bf16 v[94:97], v[134:137], v[188:191], v[94:97]
	v_mfma_f32_16x16x32_bf16 v[90:93], v[142:145], v[188:191], v[90:93]
	s_waitcnt lgkmcnt(0)
	v_mfma_f32_16x16x32_bf16 v[74:77], v[142:145], v[200:203], v[74:77]
	v_mfma_f32_16x16x32_bf16 v[78:81], v[134:137], v[200:203], v[78:81]
	s_setprio 0
	s_setprio 1
	v_mfma_f32_16x16x32_bf16 v[118:121], v[146:149], v[168:171], v[118:121]
	v_mfma_f32_16x16x32_bf16 v[114:117], v[154:157], v[168:171], v[114:117]
	v_mfma_f32_16x16x32_bf16 v[98:101], v[154:157], v[176:179], v[98:101]
	v_mfma_f32_16x16x32_bf16 v[102:105], v[146:149], v[176:179], v[102:105]
	v_mfma_f32_16x16x32_bf16 v[86:89], v[146:149], v[184:187], v[86:89]
	v_mfma_f32_16x16x32_bf16 v[82:85], v[154:157], v[184:187], v[82:85]
	v_mfma_f32_16x16x32_bf16 v[66:69], v[154:157], v[192:195], v[66:69]
	v_mfma_f32_16x16x32_bf16 v[70:73], v[146:149], v[192:195], v[70:73]
	v_mfma_f32_16x16x32_bf16 v[118:121], v[150:153], v[172:175], v[118:121]
	v_mfma_f32_16x16x32_bf16 v[114:117], v[164:167], v[172:175], v[114:117]
	v_mfma_f32_16x16x32_bf16 v[98:101], v[164:167], v[180:183], v[98:101]
	v_mfma_f32_16x16x32_bf16 v[102:105], v[150:153], v[180:183], v[102:105]
	v_mfma_f32_16x16x32_bf16 v[86:89], v[150:153], v[188:191], v[86:89]
	v_mfma_f32_16x16x32_bf16 v[82:85], v[164:167], v[188:191], v[82:85]
	v_mfma_f32_16x16x32_bf16 v[66:69], v[164:167], v[200:203], v[66:69]
	v_mfma_f32_16x16x32_bf16 v[70:73], v[150:153], v[200:203], v[70:73]
	s_setprio 0
	s_barrier
; #define PG8_WAIT_V(n) asm volatile("s_waitcnt vmcnt(" #n ")" ::: "memory")
; template <class Epi, bool ALIGN_EPI, bool SP2, class Hook>
; __device__ __forceinline__ void gemm_phase(LAS unsigned char* lds, const Gemm g, const StaticOrder& S, const Epi& E, Acc& acc, const bool fresh, const Hook& H, const int wave_id) {
;     ...
;         for (int t = t0; t < nt; t += 2) {
;             const bool last = (t == nt - 2);
;             const Src a1 = cA + (size_t)(t + 1) * kstep;
;             const Src a2 = last ? nA : cA + (size_t)(t + 2) * kstep, b2 = last ? nB : cB + (size_t)(t + 2) * kstep;
;             const Src a3 = a2 + kstep, b3 = b2 + kstep;
;             if (last && has_next) H(nxt);
;             if constexpr (SP2) {
;             PG8_TRIP_SP2(PG8_WAIT_V(8));
	s_mov_b32 m0, s39
	s_or_b32 s64, s62, 0x80
	ds_read_b128 v[168:171], v162 offset:49152
	ds_read_b128 v[172:175], v162 offset:50176
	ds_read_b128 v[176:179], v162 offset:51200
	ds_read_b128 v[180:183], v162 offset:52224
	ds_read_b128 v[184:187], v162 offset:53248
	ds_read_b128 v[188:191], v162 offset:54272
	ds_read_b128 v[192:195], v162 offset:55296
	ds_read_b128 v[200:203], v162 offset:56320
	buffer_load_dwordx4 v158, s[16:19], s64 offen lds
	s_mov_b32 m0, s40
	s_add_i32 s62, s62, 0xb0080
	buffer_load_dwordx4 v160, s[16:19], s64 offen lds
	s_mov_b32 m0, s43
	s_nop 0
	buffer_load_dwordx4 v158, s[16:19], s62 offen lds
	s_mov_b32 m0, s42
	s_nop 0
	buffer_load_dwordx4 v160, s[16:19], s62 offen lds
	s_mov_b32 m0, s41
	s_nop 0
	buffer_load_dwordx4 v0, s[20:23], s63 offen lds
	s_mov_b32 m0, s33
	s_nop 0
	buffer_load_dwordx4 v159, s[20:23], s63 offen lds
	s_waitcnt vmcnt(8)
	s_waitcnt lgkmcnt(0)
	s_barrier
	s_setprio 1
	s_waitcnt lgkmcnt(7)
	v_mfma_f32_16x16x32_bf16 v[62:65], v[130:133], v[168:171], v[62:65]
	v_mfma_f32_16x16x32_bf16 v[58:61], v[138:141], v[168:171], v[58:61]
	s_waitcnt lgkmcnt(5)
	v_mfma_f32_16x16x32_bf16 v[42:45], v[138:141], v[176:179], v[42:45]
	v_mfma_f32_16x16x32_bf16 v[46:49], v[130:133], v[176:179], v[46:49]
	s_waitcnt lgkmcnt(3)
	v_mfma_f32_16x16x32_bf16 v[30:33], v[130:133], v[184:187], v[30:33]
	v_mfma_f32_16x16x32_bf16 v[26:29], v[138:141], v[184:187], v[26:29]
	s_waitcnt lgkmcnt(1)
	v_mfma_f32_16x16x32_bf16 v[10:13], v[138:141], v[192:195], v[10:13]
	v_mfma_f32_16x16x32_bf16 v[14:17], v[130:133], v[192:195], v[14:17]
	v_mfma_f32_16x16x32_bf16 v[62:65], v[134:137], v[172:175], v[62:65]
	v_mfma_f32_16x16x32_bf16 v[58:61], v[142:145], v[172:175], v[58:61]
	v_mfma_f32_16x16x32_bf16 v[42:45], v[142:145], v[180:183], v[42:45]
	v_mfma_f32_16x16x32_bf16 v[46:49], v[134:137], v[180:183], v[46:49]
	v_mfma_f32_16x16x32_bf16 v[30:33], v[134:137], v[188:191], v[30:33]
	v_mfma_f32_16x16x32_bf16 v[26:29], v[142:145], v[188:191], v[26:29]
	s_waitcnt lgkmcnt(0)
	v_mfma_f32_16x16x32_bf16 v[10:13], v[142:145], v[200:203], v[10:13]
	v_mfma_f32_16x16x32_bf16 v[14:17], v[134:137], v[200:203], v[14:17]
	s_setprio 0
	s_setprio 1
	v_mfma_f32_16x16x32_bf16 v[54:57], v[146:149], v[168:171], v[54:57]
	v_mfma_f32_16x16x32_bf16 v[50:53], v[154:157], v[168:171], v[50:53]
	v_mfma_f32_16x16x32_bf16 v[34:37], v[154:157], v[176:179], v[34:37]
	v_mfma_f32_16x16x32_bf16 v[38:41], v[146:149], v[176:179], v[38:41]
	v_mfma_f32_16x16x32_bf16 v[22:25], v[146:149], v[184:187], v[22:25]
	v_mfma_f32_16x16x32_bf16 v[18:21], v[154:157], v[184:187], v[18:21]
	v_mfma_f32_16x16x32_bf16 v[2:5], v[154:157], v[192:195], v[2:5]
	v_mfma_f32_16x16x32_bf16 v[6:9], v[146:149], v[192:195], v[6:9]
	v_mfma_f32_16x16x32_bf16 v[54:57], v[150:153], v[172:175], v[54:57]
	v_mfma_f32_16x16x32_bf16 v[50:53], v[164:167], v[172:175], v[50:53]
	v_mfma_f32_16x16x32_bf16 v[34:37], v[164:167], v[180:183], v[34:37]
	v_mfma_f32_16x16x32_bf16 v[38:41], v[150:153], v[180:183], v[38:41]
	v_mfma_f32_16x16x32_bf16 v[22:25], v[150:153], v[188:191], v[22:25]
	v_mfma_f32_16x16x32_bf16 v[18:21], v[164:167], v[188:191], v[18:21]
	v_mfma_f32_16x16x32_bf16 v[2:5], v[164:167], v[200:203], v[2:5]
	v_mfma_f32_16x16x32_bf16 v[6:9], v[150:153], v[200:203], v[6:9]
	s_setprio 0
	s_barrier
	s_add_i32 s61, s61, 2
	s_addk_i32 s2, 0x100
	s_addk_i32 s3, 0x100
	s_cmp_gt_u32 s61, 41
	s_cbranch_scc0 .LBB0_1572
	v_readlane_b32 s2, v251, 45
	v_readlane_b32 s3, v251, 46
	s_and_b64 vcc, exec, s[2:3]
	s_cbranch_vccz .LBB0_1575
	s_barrier

; #define PG8_WAIT_V(n) asm volatile("s_waitcnt vmcnt(" #n ")" ::: "memory")
; template <class Epi, bool ALIGN_EPI, bool SP2, class Hook>
; __device__ __forceinline__ void gemm_phase(LAS unsigned char* lds, const Gemm g, const StaticOrder& S, const Epi& E, Acc& acc, const bool fresh, const Hook& H, const int wave_id) {
;     ...
;         for (int t = t0; t < nt; t += 2) {
;             const bool last = (t == nt - 2);
;             const Src a1 = cA + (size_t)(t + 1) * kstep;
;             const Src a2 = last ? nA : cA + (size_t)(t + 2) * kstep, b2 = last ? nB : cB + (size_t)(t + 2) * kstep;
;             const Src a3 = a2 + kstep, b3 = b2 + kstep;
;             if (last && has_next) H(nxt);
;             if constexpr (SP2) {
;             PG8_TRIP_SP2(PG8_WAIT_V(8));
.LBB0_1614:
	v_add_u32_e32 v0, 0x10000, v172
	ds_read_b128 v[130:133], v0
	ds_read_b128 v[134:137], v0 offset:1024
	ds_read_b128 v[138:141], v0 offset:2048
	ds_read_b128 v[142:145], v0 offset:3072
	v_add_u32_e32 v0, 0x14000, v172
	ds_read_b128 v[146:149], v0
	ds_read_b128 v[150:153], v0 offset:1024
	ds_read_b128 v[154:157], v0 offset:2048
	ds_read_b128 v[158:161], v0 offset:3072
	s_add_i32 s12, s2, 0xfff40080
	s_cmp_eq_u32 s59, 40
	s_cselect_b32 s62, s55, s12
	s_cselect_b32 s13, s31, s77
	s_cselect_b32 s12, s30, s76
	s_cselect_b32 s15, s35, s51
	s_cselect_b32 s14, s34, s50
	s_cselect_b32 s60, s56, s3
	s_cselect_b32 s16, s20, s8
	s_cselect_b32 s17, s21, s9
	s_cselect_b32 s18, s22, s10
	s_cselect_b32 s19, s23, s11
	s_or_b32 s61, s62, 0x80
	s_mov_b32 m0, s45
	ds_read_b128 v[162:165], v173
	ds_read_b128 v[174:177], v173 offset:1024
	ds_read_b128 v[178:181], v173 offset:2048
	ds_read_b128 v[182:185], v173 offset:3072
	ds_read_b128 v[186:189], v173 offset:4096
	ds_read_b128 v[190:193], v173 offset:5120
	ds_read_b128 v[194:197], v173 offset:6144
	ds_read_b128 v[200:203], v173 offset:7168
	buffer_load_dwordx4 v168, s[8:11], s2 offen lds
	s_mov_b32 m0, s46
	s_nop 0
	buffer_load_dwordx4 v170, s[8:11], s2 offen lds
	s_waitcnt vmcnt(8)
	s_waitcnt lgkmcnt(0)
	s_barrier
	s_setprio 1
	s_waitcnt lgkmcnt(7)
	v_mfma_f32_16x16x32_bf16 v[126:129], v[130:133], v[162:165], v[126:129]
	v_mfma_f32_16x16x32_bf16 v[122:125], v[138:141], v[162:165], v[122:125]
	s_waitcnt lgkmcnt(5)
	v_mfma_f32_16x16x32_bf16 v[106:109], v[138:141], v[178:181], v[106:109]
	v_mfma_f32_16x16x32_bf16 v[110:113], v[130:133], v[178:181], v[110:113]
	s_waitcnt lgkmcnt(3)
	v_mfma_f32_16x16x32_bf16 v[94:97], v[130:133], v[186:189], v[94:97]
	v_mfma_f32_16x16x32_bf16 v[90:93], v[138:141], v[186:189], v[90:93]
	s_waitcnt lgkmcnt(1)
	v_mfma_f32_16x16x32_bf16 v[74:77], v[138:141], v[194:197], v[74:77]
	v_mfma_f32_16x16x32_bf16 v[78:81], v[130:133], v[194:197], v[78:81]
	v_mfma_f32_16x16x32_bf16 v[126:129], v[134:137], v[174:177], v[126:129]
	v_mfma_f32_16x16x32_bf16 v[122:125], v[142:145], v[174:177], v[122:125]
	v_mfma_f32_16x16x32_bf16 v[106:109], v[142:145], v[182:185], v[106:109]
	v_mfma_f32_16x16x32_bf16 v[110:113], v[134:137], v[182:185], v[110:113]
	v_mfma_f32_16x16x32_bf16 v[94:97], v[134:137], v[190:193], v[94:97]
	v_mfma_f32_16x16x32_bf16 v[90:93], v[142:145], v[190:193], v[90:93]
	s_waitcnt lgkmcnt(0)
	v_mfma_f32_16x16x32_bf16 v[74:77], v[142:145], v[200:203], v[74:77]
	v_mfma_f32_16x16x32_bf16 v[78:81], v[134:137], v[200:203], v[78:81]
	s_setprio 0
	s_setprio 1
	v_mfma_f32_16x16x32_bf16 v[118:121], v[146:149], v[162:165], v[118:121]
	v_mfma_f32_16x16x32_bf16 v[114:117], v[154:157], v[162:165], v[114:117]
	v_mfma_f32_16x16x32_bf16 v[98:101], v[154:157], v[178:181], v[98:101]
	v_mfma_f32_16x16x32_bf16 v[102:105], v[146:149], v[178:181], v[102:105]
	v_mfma_f32_16x16x32_bf16 v[86:89], v[146:149], v[186:189], v[86:89]
	v_mfma_f32_16x16x32_bf16 v[82:85], v[154:157], v[186:189], v[82:85]
	v_mfma_f32_16x16x32_bf16 v[66:69], v[154:157], v[194:197], v[66:69]
	v_mfma_f32_16x16x32_bf16 v[70:73], v[146:149], v[194:197], v[70:73]
	v_mfma_f32_16x16x32_bf16 v[118:121], v[150:153], v[174:177], v[118:121]
	v_mfma_f32_16x16x32_bf16 v[114:117], v[158:161], v[174:177], v[114:117]
	v_mfma_f32_16x16x32_bf16 v[98:101], v[158:161], v[182:185], v[98:101]
	v_mfma_f32_16x16x32_bf16 v[102:105], v[150:153], v[182:185], v[102:105]
	v_mfma_f32_16x16x32_bf16 v[86:89], v[150:153], v[190:193], v[86:89]
	v_mfma_f32_16x16x32_bf16 v[82:85], v[158:161], v[190:193], v[82:85]
	v_mfma_f32_16x16x32_bf16 v[66:69], v[158:161], v[200:203], v[66:69]
	v_mfma_f32_16x16x32_bf16 v[70:73], v[150:153], v[200:203], v[70:73]
	s_setprio 0
	s_barrier
	s_mov_b32 m0, s92
	ds_read_b128 v[162:165], v173 offset:16384
	ds_read_b128 v[174:177], v173 offset:17408
	ds_read_b128 v[178:181], v173 offset:18432
	ds_read_b128 v[182:185], v173 offset:19456
	ds_read_b128 v[186:189], v173 offset:20480
	ds_read_b128 v[190:193], v173 offset:21504
	ds_read_b128 v[194:197], v173 offset:22528
	ds_read_b128 v[200:203], v173 offset:23552
	buffer_load_dwordx4 v169, s[12:15], s60 offen lds
	s_mov_b32 m0, s93
	s_add_i32 s63, s60, 0xb0000
	buffer_load_dwordx4 v171, s[12:15], s60 offen lds
	s_mov_b32 m0, s94
	s_nop 0
	buffer_load_dwordx4 v169, s[12:15], s63 offen lds
	s_mov_b32 m0, s95
	s_nop 0
	buffer_load_dwordx4 v171, s[12:15], s63 offen lds
	s_mov_b32 m0, s44
	s_nop 0
	buffer_load_dwordx4 v168, s[16:19], s62 offen lds
	s_mov_b32 m0, s36
	s_nop 0
	buffer_load_dwordx4 v170, s[16:19], s62 offen lds
	s_waitcnt vmcnt(8)
	s_waitcnt lgkmcnt(0)
	s_barrier
; #define PG8_WAIT_V(n) asm volatile("s_waitcnt vmcnt(" #n ")" ::: "memory")
; template <class Epi, bool ALIGN_EPI, bool SP2, class Hook>
; __device__ __forceinline__ void gemm_phase(LAS unsigned char* lds, const Gemm g, const StaticOrder& S, const Epi& E, Acc& acc, const bool fresh, const Hook& H, const int wave_id) {
;     ...
;         for (int t = t0; t < nt; t += 2) {
;             const bool last = (t == nt - 2);
;             const Src a1 = cA + (size_t)(t + 1) * kstep;
;             const Src a2 = last ? nA : cA + (size_t)(t + 2) * kstep, b2 = last ? nB : cB + (size_t)(t + 2) * kstep;
;             const Src a3 = a2 + kstep, b3 = b2 + kstep;
;             if (last && has_next) H(nxt);
;             if constexpr (SP2) {
;             PG8_TRIP_SP2(PG8_WAIT_V(8));
	s_setprio 1
	s_waitcnt lgkmcnt(7)
	v_mfma_f32_16x16x32_bf16 v[62:65], v[130:133], v[162:165], v[62:65]
	v_mfma_f32_16x16x32_bf16 v[58:61], v[138:141], v[162:165], v[58:61]
	s_waitcnt lgkmcnt(5)
	v_mfma_f32_16x16x32_bf16 v[42:45], v[138:141], v[178:181], v[42:45]
	v_mfma_f32_16x16x32_bf16 v[46:49], v[130:133], v[178:181], v[46:49]
	s_waitcnt lgkmcnt(3)
	v_mfma_f32_16x16x32_bf16 v[30:33], v[130:133], v[186:189], v[30:33]
	v_mfma_f32_16x16x32_bf16 v[26:29], v[138:141], v[186:189], v[26:29]
	s_waitcnt lgkmcnt(1)
	v_mfma_f32_16x16x32_bf16 v[10:13], v[138:141], v[194:197], v[10:13]
	v_mfma_f32_16x16x32_bf16 v[14:17], v[130:133], v[194:197], v[14:17]
	v_mfma_f32_16x16x32_bf16 v[62:65], v[134:137], v[174:177], v[62:65]
	v_mfma_f32_16x16x32_bf16 v[58:61], v[142:145], v[174:177], v[58:61]
	v_mfma_f32_16x16x32_bf16 v[42:45], v[142:145], v[182:185], v[42:45]
	v_mfma_f32_16x16x32_bf16 v[46:49], v[134:137], v[182:185], v[46:49]
	v_mfma_f32_16x16x32_bf16 v[30:33], v[134:137], v[190:193], v[30:33]
	v_mfma_f32_16x16x32_bf16 v[26:29], v[142:145], v[190:193], v[26:29]
	s_waitcnt lgkmcnt(0)
	v_mfma_f32_16x16x32_bf16 v[10:13], v[142:145], v[200:203], v[10:13]
	v_mfma_f32_16x16x32_bf16 v[14:17], v[134:137], v[200:203], v[14:17]
	s_setprio 0
	s_setprio 1
	v_mfma_f32_16x16x32_bf16 v[54:57], v[146:149], v[162:165], v[54:57]
	v_mfma_f32_16x16x32_bf16 v[50:53], v[154:157], v[162:165], v[50:53]
	v_mfma_f32_16x16x32_bf16 v[34:37], v[154:157], v[178:181], v[34:37]
	v_mfma_f32_16x16x32_bf16 v[38:41], v[146:149], v[178:181], v[38:41]
	v_mfma_f32_16x16x32_bf16 v[22:25], v[146:149], v[186:189], v[22:25]
	v_mfma_f32_16x16x32_bf16 v[18:21], v[154:157], v[186:189], v[18:21]
	v_mfma_f32_16x16x32_bf16 v[2:5], v[154:157], v[194:197], v[2:5]
	v_mfma_f32_16x16x32_bf16 v[6:9], v[146:149], v[194:197], v[6:9]
	v_mfma_f32_16x16x32_bf16 v[54:57], v[150:153], v[174:177], v[54:57]
	v_mfma_f32_16x16x32_bf16 v[50:53], v[158:161], v[174:177], v[50:53]
	v_mfma_f32_16x16x32_bf16 v[34:37], v[158:161], v[182:185], v[34:37]
	v_mfma_f32_16x16x32_bf16 v[38:41], v[150:153], v[182:185], v[38:41]
	v_mfma_f32_16x16x32_bf16 v[22:25], v[150:153], v[190:193], v[22:25]
	v_mfma_f32_16x16x32_bf16 v[18:21], v[158:161], v[190:193], v[18:21]
	v_mfma_f32_16x16x32_bf16 v[2:5], v[158:161], v[200:203], v[2:5]
	v_mfma_f32_16x16x32_bf16 v[6:9], v[150:153], v[200:203], v[6:9]
	s_setprio 0
	s_barrier
	v_add_u32_e32 v0, 0x18000, v172
	ds_read_b128 v[130:133], v0
	ds_read_b128 v[134:137], v0 offset:1024
	ds_read_b128 v[138:141], v0 offset:2048
	ds_read_b128 v[142:145], v0 offset:3072
	v_add_u32_e32 v0, 0x1c000, v172
	ds_read_b128 v[146:149], v0
	ds_read_b128 v[150:153], v0 offset:1024
	ds_read_b128 v[154:157], v0 offset:2048
	ds_read_b128 v[158:161], v0 offset:3072
	s_add_i32 s62, s62, 0xc0000
	s_mov_b32 m0, s37
	ds_read_b128 v[162:165], v173 offset:32768
	ds_read_b128 v[174:177], v173 offset:33792
	ds_read_b128 v[178:181], v173 offset:34816
	ds_read_b128 v[182:185], v173 offset:35840
	ds_read_b128 v[186:189], v173 offset:36864
	ds_read_b128 v[190:193], v173 offset:37888
	ds_read_b128 v[194:197], v173 offset:38912
	ds_read_b128 v[200:203], v173 offset:39936
	buffer_load_dwordx4 v168, s[16:19], s62 offen lds
	s_mov_b32 m0, s38
	s_nop 0
	buffer_load_dwordx4 v170, s[16:19], s62 offen lds
	s_waitcnt vmcnt(8)
	s_waitcnt lgkmcnt(0)
	s_barrier
	s_setprio 1
	s_waitcnt lgkmcnt(7)
	v_mfma_f32_16x16x32_bf16 v[126:129], v[130:133], v[162:165], v[126:129]
	v_mfma_f32_16x16x32_bf16 v[122:125], v[138:141], v[162:165], v[122:125]
	s_waitcnt lgkmcnt(5)
	v_mfma_f32_16x16x32_bf16 v[106:109], v[138:141], v[178:181], v[106:109]
	v_mfma_f32_16x16x32_bf16 v[110:113], v[130:133], v[178:181], v[110:113]
	s_waitcnt lgkmcnt(3)
	v_mfma_f32_16x16x32_bf16 v[94:97], v[130:133], v[186:189], v[94:97]
	v_mfma_f32_16x16x32_bf16 v[90:93], v[138:141], v[186:189], v[90:93]
	s_waitcnt lgkmcnt(1)
	v_mfma_f32_16x16x32_bf16 v[74:77], v[138:141], v[194:197], v[74:77]
	v_mfma_f32_16x16x32_bf16 v[78:81], v[130:133], v[194:197], v[78:81]
	v_mfma_f32_16x16x32_bf16 v[126:129], v[134:137], v[174:177], v[126:129]
	v_mfma_f32_16x16x32_bf16 v[122:125], v[142:145], v[174:177], v[122:125]
	v_mfma_f32_16x16x32_bf16 v[106:109], v[142:145], v[182:185], v[106:109]
	v_mfma_f32_16x16x32_bf16 v[110:113], v[134:137], v[182:185], v[110:113]
	v_mfma_f32_16x16x32_bf16 v[94:97], v[134:137], v[190:193], v[94:97]
	v_mfma_f32_16x16x32_bf16 v[90:93], v[142:145], v[190:193], v[90:93]
	s_waitcnt lgkmcnt(0)
	v_mfma_f32_16x16x32_bf16 v[74:77], v[142:145], v[200:203], v[74:77]
	v_mfma_f32_16x16x32_bf16 v[78:81], v[134:137], v[200:203], v[78:81]
	s_setprio 0
	s_setprio 1
	v_mfma_f32_16x16x32_bf16 v[118:121], v[146:149], v[162:165], v[118:121]
	v_mfma_f32_16x16x32_bf16 v[114:117], v[154:157], v[162:165], v[114:117]
	v_mfma_f32_16x16x32_bf16 v[98:101], v[154:157], v[178:181], v[98:101]
	v_mfma_f32_16x16x32_bf16 v[102:105], v[146:149], v[178:181], v[102:105]
	v_mfma_f32_16x16x32_bf16 v[86:89], v[146:149], v[186:189], v[86:89]
	v_mfma_f32_16x16x32_bf16 v[82:85], v[154:157], v[186:189], v[82:85]
	v_mfma_f32_16x16x32_bf16 v[66:69], v[154:157], v[194:197], v[66:69]
	v_mfma_f32_16x16x32_bf16 v[70:73], v[146:149], v[194:197], v[70:73]
	v_mfma_f32_16x16x32_bf16 v[118:121], v[150:153], v[174:177], v[118:121]
	v_mfma_f32_16x16x32_bf16 v[114:117], v[158:161], v[174:177], v[114:117]
	v_mfma_f32_16x16x32_bf16 v[98:101], v[158:161], v[182:185], v[98:101]
	v_mfma_f32_16x16x32_bf16 v[102:105], v[150:153], v[182:185], v[102:105]
	v_mfma_f32_16x16x32_bf16 v[86:89], v[150:153], v[190:193], v[86:89]
	v_mfma_f32_16x16x32_bf16 v[82:85], v[158:161], v[190:193], v[82:85]
	v_mfma_f32_16x16x32_bf16 v[66:69], v[158:161], v[200:203], v[66:69]
	v_mfma_f32_16x16x32_bf16 v[70:73], v[150:153], v[200:203], v[70:73]
	s_setprio 0
	s_barrier
; #define PG8_WAIT_V(n) asm volatile("s_waitcnt vmcnt(" #n ")" ::: "memory")
; template <class Epi, bool ALIGN_EPI, bool SP2, class Hook>
; __device__ __forceinline__ void gemm_phase(LAS unsigned char* lds, const Gemm g, const StaticOrder& S, const Epi& E, Acc& acc, const bool fresh, const Hook& H, const int wave_id) {
;     ...
;         for (int t = t0; t < nt; t += 2) {
;             const bool last = (t == nt - 2);
;             const Src a1 = cA + (size_t)(t + 1) * kstep;
;             const Src a2 = last ? nA : cA + (size_t)(t + 2) * kstep, b2 = last ? nB : cB + (size_t)(t + 2) * kstep;
;             const Src a3 = a2 + kstep, b3 = b2 + kstep;
;             if (last && has_next) H(nxt);
;             if constexpr (SP2) {
;             PG8_TRIP_SP2(PG8_WAIT_V(8));
	s_mov_b32 m0, s39
	s_or_b32 s62, s60, 0x80
	ds_read_b128 v[162:165], v173 offset:49152
	ds_read_b128 v[174:177], v173 offset:50176
	ds_read_b128 v[178:181], v173 offset:51200
	ds_read_b128 v[182:185], v173 offset:52224
	ds_read_b128 v[186:189], v173 offset:53248
	ds_read_b128 v[190:193], v173 offset:54272
	ds_read_b128 v[194:197], v173 offset:55296
	ds_read_b128 v[200:203], v173 offset:56320
	buffer_load_dwordx4 v169, s[12:15], s62 offen lds
	s_mov_b32 m0, s40
	s_add_i32 s60, s60, 0xb0080
	buffer_load_dwordx4 v171, s[12:15], s62 offen lds
	s_mov_b32 m0, s43
	s_nop 0
	buffer_load_dwordx4 v169, s[12:15], s60 offen lds
	s_mov_b32 m0, s42
	s_nop 0
	buffer_load_dwordx4 v171, s[12:15], s60 offen lds
	s_mov_b32 m0, s41
	s_nop 0
	buffer_load_dwordx4 v168, s[16:19], s61 offen lds
	s_mov_b32 m0, s33
	s_nop 0
	buffer_load_dwordx4 v170, s[16:19], s61 offen lds
	s_waitcnt vmcnt(8)
	s_waitcnt lgkmcnt(0)
	s_barrier
	s_setprio 1
	s_waitcnt lgkmcnt(7)
	v_mfma_f32_16x16x32_bf16 v[62:65], v[130:133], v[162:165], v[62:65]
	v_mfma_f32_16x16x32_bf16 v[58:61], v[138:141], v[162:165], v[58:61]
	s_waitcnt lgkmcnt(5)
	v_mfma_f32_16x16x32_bf16 v[42:45], v[138:141], v[178:181], v[42:45]
	v_mfma_f32_16x16x32_bf16 v[46:49], v[130:133], v[178:181], v[46:49]
	s_waitcnt lgkmcnt(3)
	v_mfma_f32_16x16x32_bf16 v[30:33], v[130:133], v[186:189], v[30:33]
	v_mfma_f32_16x16x32_bf16 v[26:29], v[138:141], v[186:189], v[26:29]
	s_waitcnt lgkmcnt(1)
	v_mfma_f32_16x16x32_bf16 v[10:13], v[138:141], v[194:197], v[10:13]
	v_mfma_f32_16x16x32_bf16 v[14:17], v[130:133], v[194:197], v[14:17]
	v_mfma_f32_16x16x32_bf16 v[62:65], v[134:137], v[174:177], v[62:65]
	v_mfma_f32_16x16x32_bf16 v[58:61], v[142:145], v[174:177], v[58:61]
	v_mfma_f32_16x16x32_bf16 v[42:45], v[142:145], v[182:185], v[42:45]
	v_mfma_f32_16x16x32_bf16 v[46:49], v[134:137], v[182:185], v[46:49]
	v_mfma_f32_16x16x32_bf16 v[30:33], v[134:137], v[190:193], v[30:33]
	v_mfma_f32_16x16x32_bf16 v[26:29], v[142:145], v[190:193], v[26:29]
	s_waitcnt lgkmcnt(0)
	v_mfma_f32_16x16x32_bf16 v[10:13], v[142:145], v[200:203], v[10:13]
	v_mfma_f32_16x16x32_bf16 v[14:17], v[134:137], v[200:203], v[14:17]
	s_setprio 0
	s_setprio 1
	v_mfma_f32_16x16x32_bf16 v[54:57], v[146:149], v[162:165], v[54:57]
	v_mfma_f32_16x16x32_bf16 v[50:53], v[154:157], v[162:165], v[50:53]
	v_mfma_f32_16x16x32_bf16 v[34:37], v[154:157], v[178:181], v[34:37]
	v_mfma_f32_16x16x32_bf16 v[38:41], v[146:149], v[178:181], v[38:41]
	v_mfma_f32_16x16x32_bf16 v[22:25], v[146:149], v[186:189], v[22:25]
	v_mfma_f32_16x16x32_bf16 v[18:21], v[154:157], v[186:189], v[18:21]
	v_mfma_f32_16x16x32_bf16 v[2:5], v[154:157], v[194:197], v[2:5]
	v_mfma_f32_16x16x32_bf16 v[6:9], v[146:149], v[194:197], v[6:9]
	v_mfma_f32_16x16x32_bf16 v[54:57], v[150:153], v[174:177], v[54:57]
	v_mfma_f32_16x16x32_bf16 v[50:53], v[158:161], v[174:177], v[50:53]
	v_mfma_f32_16x16x32_bf16 v[34:37], v[158:161], v[182:185], v[34:37]
	v_mfma_f32_16x16x32_bf16 v[38:41], v[150:153], v[182:185], v[38:41]
	v_mfma_f32_16x16x32_bf16 v[22:25], v[150:153], v[190:193], v[22:25]
	v_mfma_f32_16x16x32_bf16 v[18:21], v[158:161], v[190:193], v[18:21]
	v_mfma_f32_16x16x32_bf16 v[2:5], v[158:161], v[200:203], v[2:5]
	v_mfma_f32_16x16x32_bf16 v[6:9], v[150:153], v[200:203], v[6:9]
	s_setprio 0
	s_barrier
	s_add_i32 s59, s59, 2
	s_addk_i32 s2, 0x100
	s_addk_i32 s3, 0x100
	s_cmp_gt_u32 s59, 41
	s_cbranch_scc0 .LBB0_1614
	v_readlane_b32 s2, v251, 45
	v_readlane_b32 s3, v251, 46
	s_and_b64 vcc, exec, s[2:3]
	s_cbranch_vccz .LBB0_1617
	s_barrier
